# v052 + weight transposes moved from the end of P1 into P0's idle workgroups (bid>=32), overlapping P0's second item round
# baseline (speedup 1.0000x reference)
.LBB0_26:
	s_mov_b64 s[34:35], 0x3000
	v_mov_b64_e32 v[18:19], v[8:9]
	global_load_dword v26, v[18:19], off
	v_lshl_add_u64 v[18:19], v[18:19], 0, s[34:35]
	global_load_dword v27, v[18:19], off
	v_lshl_add_u64 v[18:19], v[18:19], 0, s[34:35]
	global_load_dword v28, v[18:19], off
	v_lshl_add_u64 v[18:19], v[18:19], 0, s[34:35]
	global_load_dword v29, v[18:19], off
	v_lshl_add_u64 v[18:19], v[18:19], 0, s[34:35]
	global_load_dword v30, v[18:19], off
	v_lshl_add_u64 v[18:19], v[18:19], 0, s[34:35]
	global_load_dword v31, v[18:19], off
	v_lshl_add_u64 v[18:19], v[18:19], 0, s[34:35]
	global_load_dword v32, v[18:19], off
	v_lshl_add_u64 v[18:19], v[18:19], 0, s[34:35]
	global_load_dword v33, v[18:19], off
	v_lshl_add_u64 v[18:19], v[18:19], 0, s[34:35]
	global_load_dword v34, v[18:19], off
	v_lshl_add_u64 v[18:19], v[18:19], 0, s[34:35]
	global_load_dword v35, v[18:19], off
	v_lshl_add_u64 v[18:19], v[18:19], 0, s[34:35]
	global_load_dword v36, v[18:19], off
	v_lshl_add_u64 v[18:19], v[18:19], 0, s[34:35]
	global_load_dword v37, v[18:19], off
	v_lshl_add_u64 v[18:19], v[18:19], 0, s[34:35]
	global_load_dword v38, v[18:19], off
	v_lshl_add_u64 v[18:19], v[18:19], 0, s[34:35]
	global_load_dword v39, v[18:19], off
	v_lshl_add_u64 v[18:19], v[18:19], 0, s[34:35]
	global_load_dword v40, v[18:19], off
	v_lshl_add_u64 v[18:19], v[18:19], 0, s[34:35]
	global_load_dword v41, v[18:19], off
	v_lshl_add_u64 v[18:19], v[18:19], 0, s[34:35]
	v_mov_b32_e32 v20, s33
	s_add_i32 s33, s33, 64
	ds_read_b128 v[58:61], v20 offset:0
	ds_read_b128 v[62:65], v20 offset:16
	ds_read_b128 v[66:69], v20 offset:32
	ds_read_b128 v[70:73], v20 offset:48
	global_load_dword v42, v[18:19], off
	v_lshl_add_u64 v[18:19], v[18:19], 0, s[34:35]
	global_load_dword v43, v[18:19], off
	v_lshl_add_u64 v[18:19], v[18:19], 0, s[34:35]
	global_load_dword v44, v[18:19], off
	v_lshl_add_u64 v[18:19], v[18:19], 0, s[34:35]
	global_load_dword v45, v[18:19], off
	v_lshl_add_u64 v[18:19], v[18:19], 0, s[34:35]
	global_load_dword v46, v[18:19], off
	v_lshl_add_u64 v[18:19], v[18:19], 0, s[34:35]
	global_load_dword v47, v[18:19], off
	v_lshl_add_u64 v[18:19], v[18:19], 0, s[34:35]
	global_load_dword v48, v[18:19], off
	v_lshl_add_u64 v[18:19], v[18:19], 0, s[34:35]
	global_load_dword v49, v[18:19], off
	v_lshl_add_u64 v[18:19], v[18:19], 0, s[34:35]
	global_load_dword v50, v[18:19], off
	v_lshl_add_u64 v[18:19], v[18:19], 0, s[34:35]
	global_load_dword v51, v[18:19], off
	v_lshl_add_u64 v[18:19], v[18:19], 0, s[34:35]
	global_load_dword v52, v[18:19], off
	v_lshl_add_u64 v[18:19], v[18:19], 0, s[34:35]
	global_load_dword v53, v[18:19], off
	v_lshl_add_u64 v[18:19], v[18:19], 0, s[34:35]
	global_load_dword v54, v[18:19], off
	v_lshl_add_u64 v[18:19], v[18:19], 0, s[34:35]
	global_load_dword v55, v[18:19], off
	v_lshl_add_u64 v[18:19], v[18:19], 0, s[34:35]
	global_load_dword v56, v[18:19], off
	v_lshl_add_u64 v[18:19], v[18:19], 0, s[34:35]
	global_load_dword v57, v[18:19], off
	v_lshl_add_u64 v[18:19], v[18:19], 0, s[34:35]
	s_waitcnt vmcnt(16)
	ds_read_b128 v[74:77], v20 offset:4096
	ds_read_b128 v[78:81], v20 offset:4112
	ds_read_b128 v[82:85], v20 offset:4128
	ds_read_b128 v[86:89], v20 offset:4144
	s_waitcnt lgkmcnt(4)
	v_fmac_f32_e32 v12, v58, v26
	v_fmac_f32_e32 v12, v59, v27
	v_fmac_f32_e32 v12, v60, v28
	v_fmac_f32_e32 v12, v61, v29
	v_fmac_f32_e32 v12, v62, v30
	v_fmac_f32_e32 v12, v63, v31
	v_fmac_f32_e32 v12, v64, v32
	v_fmac_f32_e32 v12, v65, v33
	v_fmac_f32_e32 v12, v66, v34
	v_fmac_f32_e32 v12, v67, v35
	v_fmac_f32_e32 v12, v68, v36
	v_fmac_f32_e32 v12, v69, v37
	v_fmac_f32_e32 v12, v70, v38
	v_fmac_f32_e32 v12, v71, v39
	v_fmac_f32_e32 v12, v72, v40
	v_fmac_f32_e32 v12, v73, v41
	ds_read_b128 v[58:61], v20 offset:8192
	ds_read_b128 v[62:65], v20 offset:8208
	ds_read_b128 v[66:69], v20 offset:8224
	ds_read_b128 v[70:73], v20 offset:8240
	s_waitcnt lgkmcnt(4)
	v_fmac_f32_e32 v13, v74, v26
	v_fmac_f32_e32 v13, v75, v27
	v_fmac_f32_e32 v13, v76, v28
	v_fmac_f32_e32 v13, v77, v29
	v_fmac_f32_e32 v13, v78, v30
	v_fmac_f32_e32 v13, v79, v31
	v_fmac_f32_e32 v13, v80, v32
	v_fmac_f32_e32 v13, v81, v33
	v_fmac_f32_e32 v13, v82, v34
	v_fmac_f32_e32 v13, v83, v35
	v_fmac_f32_e32 v13, v84, v36
	v_fmac_f32_e32 v13, v85, v37
	v_fmac_f32_e32 v13, v86, v38
	v_fmac_f32_e32 v13, v87, v39
	v_fmac_f32_e32 v13, v88, v40
	v_fmac_f32_e32 v13, v89, v41
	ds_read_b128 v[74:77], v20 offset:12288
	ds_read_b128 v[78:81], v20 offset:12304
	ds_read_b128 v[82:85], v20 offset:12320
	ds_read_b128 v[86:89], v20 offset:12336
	s_waitcnt lgkmcnt(4)
	v_fmac_f32_e32 v14, v58, v26
	v_fmac_f32_e32 v14, v59, v27
	v_fmac_f32_e32 v14, v60, v28
	v_fmac_f32_e32 v14, v61, v29
	v_fmac_f32_e32 v14, v62, v30
	v_fmac_f32_e32 v14, v63, v31
	v_fmac_f32_e32 v14, v64, v32
	v_fmac_f32_e32 v14, v65, v33
	v_fmac_f32_e32 v14, v66, v34
	v_fmac_f32_e32 v14, v67, v35
	v_fmac_f32_e32 v14, v68, v36
	v_fmac_f32_e32 v14, v69, v37
	v_fmac_f32_e32 v14, v70, v38
	v_fmac_f32_e32 v14, v71, v39
	v_fmac_f32_e32 v14, v72, v40
	v_fmac_f32_e32 v14, v73, v41
	ds_read_b128 v[58:61], v20 offset:16384
	ds_read_b128 v[62:65], v20 offset:16400
	ds_read_b128 v[66:69], v20 offset:16416
	ds_read_b128 v[70:73], v20 offset:16432
	s_waitcnt lgkmcnt(4)
	v_fmac_f32_e32 v15, v74, v26
	v_fmac_f32_e32 v15, v75, v27
	v_fmac_f32_e32 v15, v76, v28
	v_fmac_f32_e32 v15, v77, v29
	v_fmac_f32_e32 v15, v78, v30
	v_fmac_f32_e32 v15, v79, v31
	v_fmac_f32_e32 v15, v80, v32
	v_fmac_f32_e32 v15, v81, v33
	v_fmac_f32_e32 v15, v82, v34
	v_fmac_f32_e32 v15, v83, v35
	v_fmac_f32_e32 v15, v84, v36
	v_fmac_f32_e32 v15, v85, v37
	v_fmac_f32_e32 v15, v86, v38
	v_fmac_f32_e32 v15, v87, v39
	v_fmac_f32_e32 v15, v88, v40
	v_fmac_f32_e32 v15, v89, v41
	ds_read_b128 v[74:77], v20 offset:20480
	ds_read_b128 v[78:81], v20 offset:20496
	ds_read_b128 v[82:85], v20 offset:20512
	ds_read_b128 v[86:89], v20 offset:20528
	s_waitcnt lgkmcnt(4)
	v_fmac_f32_e32 v16, v58, v26
	v_fmac_f32_e32 v16, v59, v27
	v_fmac_f32_e32 v16, v60, v28
	v_fmac_f32_e32 v16, v61, v29
	v_fmac_f32_e32 v16, v62, v30
	v_fmac_f32_e32 v16, v63, v31
	v_fmac_f32_e32 v16, v64, v32
	v_fmac_f32_e32 v16, v65, v33
	v_fmac_f32_e32 v16, v66, v34
	v_fmac_f32_e32 v16, v67, v35
	v_fmac_f32_e32 v16, v68, v36
	v_fmac_f32_e32 v16, v69, v37
	v_fmac_f32_e32 v16, v70, v38
	v_fmac_f32_e32 v16, v71, v39
	v_fmac_f32_e32 v16, v72, v40
	v_fmac_f32_e32 v16, v73, v41
	ds_read_b128 v[58:61], v20 offset:24576
	ds_read_b128 v[62:65], v20 offset:24592
	ds_read_b128 v[66:69], v20 offset:24608
	ds_read_b128 v[70:73], v20 offset:24624
	s_waitcnt lgkmcnt(4)
	v_fmac_f32_e32 v17, v74, v26
	v_fmac_f32_e32 v17, v75, v27
	v_fmac_f32_e32 v17, v76, v28
	v_fmac_f32_e32 v17, v77, v29
	v_fmac_f32_e32 v17, v78, v30
	v_fmac_f32_e32 v17, v79, v31
	v_fmac_f32_e32 v17, v80, v32
	v_fmac_f32_e32 v17, v81, v33
	v_fmac_f32_e32 v17, v82, v34
	v_fmac_f32_e32 v17, v83, v35
	v_fmac_f32_e32 v17, v84, v36
	v_fmac_f32_e32 v17, v85, v37
	v_fmac_f32_e32 v17, v86, v38
	v_fmac_f32_e32 v17, v87, v39
	v_fmac_f32_e32 v17, v88, v40
	v_fmac_f32_e32 v17, v89, v41
	ds_read_b128 v[74:77], v20 offset:28672
	ds_read_b128 v[78:81], v20 offset:28688
	ds_read_b128 v[82:85], v20 offset:28704
	ds_read_b128 v[86:89], v20 offset:28720
	s_waitcnt lgkmcnt(4)
	v_fmac_f32_e32 v10, v58, v26
	v_fmac_f32_e32 v10, v59, v27
	v_fmac_f32_e32 v10, v60, v28
	v_fmac_f32_e32 v10, v61, v29
	v_fmac_f32_e32 v10, v62, v30
	v_fmac_f32_e32 v10, v63, v31
	v_fmac_f32_e32 v10, v64, v32
	v_fmac_f32_e32 v10, v65, v33
	v_fmac_f32_e32 v10, v66, v34
	v_fmac_f32_e32 v10, v67, v35
	v_fmac_f32_e32 v10, v68, v36
	v_fmac_f32_e32 v10, v69, v37
	v_fmac_f32_e32 v10, v70, v38
	v_fmac_f32_e32 v10, v71, v39
	v_fmac_f32_e32 v10, v72, v40
	v_fmac_f32_e32 v10, v73, v41
	s_waitcnt lgkmcnt(0)
	v_fmac_f32_e32 v11, v74, v26
	v_fmac_f32_e32 v11, v75, v27
	v_fmac_f32_e32 v11, v76, v28
	v_fmac_f32_e32 v11, v77, v29
	v_fmac_f32_e32 v11, v78, v30
	v_fmac_f32_e32 v11, v79, v31
	v_fmac_f32_e32 v11, v80, v32
	v_fmac_f32_e32 v11, v81, v33
	v_fmac_f32_e32 v11, v82, v34
	v_fmac_f32_e32 v11, v83, v35
	v_fmac_f32_e32 v11, v84, v36
	v_fmac_f32_e32 v11, v85, v37
	v_fmac_f32_e32 v11, v86, v38
	v_fmac_f32_e32 v11, v87, v39
	v_fmac_f32_e32 v11, v88, v40
	v_fmac_f32_e32 v11, v89, v41
	v_mov_b32_e32 v20, s33
	s_add_i32 s33, s33, 64
	ds_read_b128 v[58:61], v20 offset:0
	ds_read_b128 v[62:65], v20 offset:16
	ds_read_b128 v[66:69], v20 offset:32
	ds_read_b128 v[70:73], v20 offset:48
	global_load_dword v26, v[18:19], off
	v_lshl_add_u64 v[18:19], v[18:19], 0, s[34:35]
	global_load_dword v27, v[18:19], off
	v_lshl_add_u64 v[18:19], v[18:19], 0, s[34:35]
	global_load_dword v28, v[18:19], off
	v_lshl_add_u64 v[18:19], v[18:19], 0, s[34:35]
	global_load_dword v29, v[18:19], off
	v_lshl_add_u64 v[18:19], v[18:19], 0, s[34:35]
	global_load_dword v30, v[18:19], off
	v_lshl_add_u64 v[18:19], v[18:19], 0, s[34:35]
	global_load_dword v31, v[18:19], off
	v_lshl_add_u64 v[18:19], v[18:19], 0, s[34:35]
	global_load_dword v32, v[18:19], off
	v_lshl_add_u64 v[18:19], v[18:19], 0, s[34:35]
	global_load_dword v33, v[18:19], off
	v_lshl_add_u64 v[18:19], v[18:19], 0, s[34:35]
	global_load_dword v34, v[18:19], off
	v_lshl_add_u64 v[18:19], v[18:19], 0, s[34:35]
	global_load_dword v35, v[18:19], off
	v_lshl_add_u64 v[18:19], v[18:19], 0, s[34:35]
	global_load_dword v36, v[18:19], off
	v_lshl_add_u64 v[18:19], v[18:19], 0, s[34:35]
	global_load_dword v37, v[18:19], off
	v_lshl_add_u64 v[18:19], v[18:19], 0, s[34:35]
	global_load_dword v38, v[18:19], off
	v_lshl_add_u64 v[18:19], v[18:19], 0, s[34:35]
	global_load_dword v39, v[18:19], off
	v_lshl_add_u64 v[18:19], v[18:19], 0, s[34:35]
	global_load_dword v40, v[18:19], off
	v_lshl_add_u64 v[18:19], v[18:19], 0, s[34:35]
	global_load_dword v41, v[18:19], off
	v_lshl_add_u64 v[18:19], v[18:19], 0, s[34:35]
	s_waitcnt vmcnt(16)
	ds_read_b128 v[74:77], v20 offset:4096
	ds_read_b128 v[78:81], v20 offset:4112
	ds_read_b128 v[82:85], v20 offset:4128
	ds_read_b128 v[86:89], v20 offset:4144
	s_waitcnt lgkmcnt(4)
	v_fmac_f32_e32 v12, v58, v42
	v_fmac_f32_e32 v12, v59, v43
	v_fmac_f32_e32 v12, v60, v44
	v_fmac_f32_e32 v12, v61, v45
	v_fmac_f32_e32 v12, v62, v46
	v_fmac_f32_e32 v12, v63, v47
	v_fmac_f32_e32 v12, v64, v48
	v_fmac_f32_e32 v12, v65, v49
	v_fmac_f32_e32 v12, v66, v50
	v_fmac_f32_e32 v12, v67, v51
	v_fmac_f32_e32 v12, v68, v52
	v_fmac_f32_e32 v12, v69, v53
	v_fmac_f32_e32 v12, v70, v54
	v_fmac_f32_e32 v12, v71, v55
	v_fmac_f32_e32 v12, v72, v56
	v_fmac_f32_e32 v12, v73, v57
	ds_read_b128 v[58:61], v20 offset:8192
	ds_read_b128 v[62:65], v20 offset:8208
	ds_read_b128 v[66:69], v20 offset:8224
	ds_read_b128 v[70:73], v20 offset:8240
	s_waitcnt lgkmcnt(4)
	v_fmac_f32_e32 v13, v74, v42
	v_fmac_f32_e32 v13, v75, v43
	v_fmac_f32_e32 v13, v76, v44
	v_fmac_f32_e32 v13, v77, v45
	v_fmac_f32_e32 v13, v78, v46
	v_fmac_f32_e32 v13, v79, v47
	v_fmac_f32_e32 v13, v80, v48
	v_fmac_f32_e32 v13, v81, v49
	v_fmac_f32_e32 v13, v82, v50
	v_fmac_f32_e32 v13, v83, v51
	v_fmac_f32_e32 v13, v84, v52
	v_fmac_f32_e32 v13, v85, v53
	v_fmac_f32_e32 v13, v86, v54
	v_fmac_f32_e32 v13, v87, v55
	v_fmac_f32_e32 v13, v88, v56
	v_fmac_f32_e32 v13, v89, v57
	ds_read_b128 v[74:77], v20 offset:12288
	ds_read_b128 v[78:81], v20 offset:12304
	ds_read_b128 v[82:85], v20 offset:12320
	ds_read_b128 v[86:89], v20 offset:12336
	s_waitcnt lgkmcnt(4)
	v_fmac_f32_e32 v14, v58, v42
	v_fmac_f32_e32 v14, v59, v43
	v_fmac_f32_e32 v14, v60, v44
	v_fmac_f32_e32 v14, v61, v45
	v_fmac_f32_e32 v14, v62, v46
	v_fmac_f32_e32 v14, v63, v47
	v_fmac_f32_e32 v14, v64, v48
	v_fmac_f32_e32 v14, v65, v49
	v_fmac_f32_e32 v14, v66, v50
	v_fmac_f32_e32 v14, v67, v51
	v_fmac_f32_e32 v14, v68, v52
	v_fmac_f32_e32 v14, v69, v53
	v_fmac_f32_e32 v14, v70, v54
	v_fmac_f32_e32 v14, v71, v55
	v_fmac_f32_e32 v14, v72, v56
	v_fmac_f32_e32 v14, v73, v57
	ds_read_b128 v[58:61], v20 offset:16384
	ds_read_b128 v[62:65], v20 offset:16400
	ds_read_b128 v[66:69], v20 offset:16416
	ds_read_b128 v[70:73], v20 offset:16432
	s_waitcnt lgkmcnt(4)
	v_fmac_f32_e32 v15, v74, v42
	v_fmac_f32_e32 v15, v75, v43
	v_fmac_f32_e32 v15, v76, v44
	v_fmac_f32_e32 v15, v77, v45
	v_fmac_f32_e32 v15, v78, v46
	v_fmac_f32_e32 v15, v79, v47
	v_fmac_f32_e32 v15, v80, v48
	v_fmac_f32_e32 v15, v81, v49
	v_fmac_f32_e32 v15, v82, v50
	v_fmac_f32_e32 v15, v83, v51
	v_fmac_f32_e32 v15, v84, v52
	v_fmac_f32_e32 v15, v85, v53
	v_fmac_f32_e32 v15, v86, v54
	v_fmac_f32_e32 v15, v87, v55
	v_fmac_f32_e32 v15, v88, v56
	v_fmac_f32_e32 v15, v89, v57
	ds_read_b128 v[74:77], v20 offset:20480
	ds_read_b128 v[78:81], v20 offset:20496
	ds_read_b128 v[82:85], v20 offset:20512
	ds_read_b128 v[86:89], v20 offset:20528
	s_waitcnt lgkmcnt(4)
	v_fmac_f32_e32 v16, v58, v42
	v_fmac_f32_e32 v16, v59, v43
	v_fmac_f32_e32 v16, v60, v44
	v_fmac_f32_e32 v16, v61, v45
	v_fmac_f32_e32 v16, v62, v46
	v_fmac_f32_e32 v16, v63, v47
	v_fmac_f32_e32 v16, v64, v48
	v_fmac_f32_e32 v16, v65, v49
	v_fmac_f32_e32 v16, v66, v50
	v_fmac_f32_e32 v16, v67, v51
	v_fmac_f32_e32 v16, v68, v52
	v_fmac_f32_e32 v16, v69, v53
	v_fmac_f32_e32 v16, v70, v54
	v_fmac_f32_e32 v16, v71, v55
	v_fmac_f32_e32 v16, v72, v56
	v_fmac_f32_e32 v16, v73, v57
	ds_read_b128 v[58:61], v20 offset:24576
	ds_read_b128 v[62:65], v20 offset:24592
	ds_read_b128 v[66:69], v20 offset:24608
	ds_read_b128 v[70:73], v20 offset:24624
	s_waitcnt lgkmcnt(4)
	v_fmac_f32_e32 v17, v74, v42
	v_fmac_f32_e32 v17, v75, v43
	v_fmac_f32_e32 v17, v76, v44
	v_fmac_f32_e32 v17, v77, v45
	v_fmac_f32_e32 v17, v78, v46
	v_fmac_f32_e32 v17, v79, v47
	v_fmac_f32_e32 v17, v80, v48
	v_fmac_f32_e32 v17, v81, v49
	v_fmac_f32_e32 v17, v82, v50
	v_fmac_f32_e32 v17, v83, v51
	v_fmac_f32_e32 v17, v84, v52
	v_fmac_f32_e32 v17, v85, v53
	v_fmac_f32_e32 v17, v86, v54
	v_fmac_f32_e32 v17, v87, v55
	v_fmac_f32_e32 v17, v88, v56
	v_fmac_f32_e32 v17, v89, v57
	ds_read_b128 v[74:77], v20 offset:28672
	ds_read_b128 v[78:81], v20 offset:28688
	ds_read_b128 v[82:85], v20 offset:28704
	ds_read_b128 v[86:89], v20 offset:28720
	s_waitcnt lgkmcnt(4)
	v_fmac_f32_e32 v10, v58, v42
	v_fmac_f32_e32 v10, v59, v43
	v_fmac_f32_e32 v10, v60, v44
	v_fmac_f32_e32 v10, v61, v45
	v_fmac_f32_e32 v10, v62, v46
	v_fmac_f32_e32 v10, v63, v47
	v_fmac_f32_e32 v10, v64, v48
	v_fmac_f32_e32 v10, v65, v49
	v_fmac_f32_e32 v10, v66, v50
	v_fmac_f32_e32 v10, v67, v51
	v_fmac_f32_e32 v10, v68, v52
	v_fmac_f32_e32 v10, v69, v53
	v_fmac_f32_e32 v10, v70, v54
	v_fmac_f32_e32 v10, v71, v55
	v_fmac_f32_e32 v10, v72, v56
	v_fmac_f32_e32 v10, v73, v57
	s_waitcnt lgkmcnt(0)
	v_fmac_f32_e32 v11, v74, v42
	v_fmac_f32_e32 v11, v75, v43
	v_fmac_f32_e32 v11, v76, v44
	v_fmac_f32_e32 v11, v77, v45
	v_fmac_f32_e32 v11, v78, v46
	v_fmac_f32_e32 v11, v79, v47
	v_fmac_f32_e32 v11, v80, v48
	v_fmac_f32_e32 v11, v81, v49
	v_fmac_f32_e32 v11, v82, v50
	v_fmac_f32_e32 v11, v83, v51
	v_fmac_f32_e32 v11, v84, v52
	v_fmac_f32_e32 v11, v85, v53
	v_fmac_f32_e32 v11, v86, v54
	v_fmac_f32_e32 v11, v87, v55
	v_fmac_f32_e32 v11, v88, v56
	v_fmac_f32_e32 v11, v89, v57
	v_mov_b32_e32 v20, s33
	s_add_i32 s33, s33, 64
	ds_read_b128 v[58:61], v20 offset:0
	ds_read_b128 v[62:65], v20 offset:16
	ds_read_b128 v[66:69], v20 offset:32
	ds_read_b128 v[70:73], v20 offset:48
	global_load_dword v42, v[18:19], off
	v_lshl_add_u64 v[18:19], v[18:19], 0, s[34:35]
	global_load_dword v43, v[18:19], off
	v_lshl_add_u64 v[18:19], v[18:19], 0, s[34:35]
	global_load_dword v44, v[18:19], off
	v_lshl_add_u64 v[18:19], v[18:19], 0, s[34:35]
	global_load_dword v45, v[18:19], off
	v_lshl_add_u64 v[18:19], v[18:19], 0, s[34:35]
	global_load_dword v46, v[18:19], off
	v_lshl_add_u64 v[18:19], v[18:19], 0, s[34:35]
	global_load_dword v47, v[18:19], off
	v_lshl_add_u64 v[18:19], v[18:19], 0, s[34:35]
	global_load_dword v48, v[18:19], off
	v_lshl_add_u64 v[18:19], v[18:19], 0, s[34:35]
	global_load_dword v49, v[18:19], off
	v_lshl_add_u64 v[18:19], v[18:19], 0, s[34:35]
	global_load_dword v50, v[18:19], off
	v_lshl_add_u64 v[18:19], v[18:19], 0, s[34:35]
	global_load_dword v51, v[18:19], off
	v_lshl_add_u64 v[18:19], v[18:19], 0, s[34:35]
	global_load_dword v52, v[18:19], off
	v_lshl_add_u64 v[18:19], v[18:19], 0, s[34:35]
	global_load_dword v53, v[18:19], off
	v_lshl_add_u64 v[18:19], v[18:19], 0, s[34:35]
	global_load_dword v54, v[18:19], off
	v_lshl_add_u64 v[18:19], v[18:19], 0, s[34:35]
	global_load_dword v55, v[18:19], off
	v_lshl_add_u64 v[18:19], v[18:19], 0, s[34:35]
	global_load_dword v56, v[18:19], off
	v_lshl_add_u64 v[18:19], v[18:19], 0, s[34:35]
	global_load_dword v57, v[18:19], off
	v_lshl_add_u64 v[18:19], v[18:19], 0, s[34:35]
	s_waitcnt vmcnt(16)
	ds_read_b128 v[74:77], v20 offset:4096
	ds_read_b128 v[78:81], v20 offset:4112
	ds_read_b128 v[82:85], v20 offset:4128
	ds_read_b128 v[86:89], v20 offset:4144
	s_waitcnt lgkmcnt(4)
	v_fmac_f32_e32 v12, v58, v26
	v_fmac_f32_e32 v12, v59, v27
	v_fmac_f32_e32 v12, v60, v28
	v_fmac_f32_e32 v12, v61, v29
	v_fmac_f32_e32 v12, v62, v30
	v_fmac_f32_e32 v12, v63, v31
	v_fmac_f32_e32 v12, v64, v32
	v_fmac_f32_e32 v12, v65, v33
	v_fmac_f32_e32 v12, v66, v34
	v_fmac_f32_e32 v12, v67, v35
	v_fmac_f32_e32 v12, v68, v36
	v_fmac_f32_e32 v12, v69, v37
	v_fmac_f32_e32 v12, v70, v38
	v_fmac_f32_e32 v12, v71, v39
	v_fmac_f32_e32 v12, v72, v40
	v_fmac_f32_e32 v12, v73, v41
	ds_read_b128 v[58:61], v20 offset:8192
	ds_read_b128 v[62:65], v20 offset:8208
	ds_read_b128 v[66:69], v20 offset:8224
	ds_read_b128 v[70:73], v20 offset:8240
	s_waitcnt lgkmcnt(4)
	v_fmac_f32_e32 v13, v74, v26
	v_fmac_f32_e32 v13, v75, v27
	v_fmac_f32_e32 v13, v76, v28
	v_fmac_f32_e32 v13, v77, v29
	v_fmac_f32_e32 v13, v78, v30
	v_fmac_f32_e32 v13, v79, v31
	v_fmac_f32_e32 v13, v80, v32
	v_fmac_f32_e32 v13, v81, v33
	v_fmac_f32_e32 v13, v82, v34
	v_fmac_f32_e32 v13, v83, v35
	v_fmac_f32_e32 v13, v84, v36
	v_fmac_f32_e32 v13, v85, v37
	v_fmac_f32_e32 v13, v86, v38
	v_fmac_f32_e32 v13, v87, v39
	v_fmac_f32_e32 v13, v88, v40
	v_fmac_f32_e32 v13, v89, v41
	ds_read_b128 v[74:77], v20 offset:12288
	ds_read_b128 v[78:81], v20 offset:12304
	ds_read_b128 v[82:85], v20 offset:12320
	ds_read_b128 v[86:89], v20 offset:12336
	s_waitcnt lgkmcnt(4)
	v_fmac_f32_e32 v14, v58, v26
	v_fmac_f32_e32 v14, v59, v27
	v_fmac_f32_e32 v14, v60, v28
	v_fmac_f32_e32 v14, v61, v29
	v_fmac_f32_e32 v14, v62, v30
	v_fmac_f32_e32 v14, v63, v31
	v_fmac_f32_e32 v14, v64, v32
	v_fmac_f32_e32 v14, v65, v33
	v_fmac_f32_e32 v14, v66, v34
	v_fmac_f32_e32 v14, v67, v35
	v_fmac_f32_e32 v14, v68, v36
	v_fmac_f32_e32 v14, v69, v37
	v_fmac_f32_e32 v14, v70, v38
	v_fmac_f32_e32 v14, v71, v39
	v_fmac_f32_e32 v14, v72, v40
	v_fmac_f32_e32 v14, v73, v41
	ds_read_b128 v[58:61], v20 offset:16384
	ds_read_b128 v[62:65], v20 offset:16400
	ds_read_b128 v[66:69], v20 offset:16416
	ds_read_b128 v[70:73], v20 offset:16432
	s_waitcnt lgkmcnt(4)
	v_fmac_f32_e32 v15, v74, v26
	v_fmac_f32_e32 v15, v75, v27
	v_fmac_f32_e32 v15, v76, v28
	v_fmac_f32_e32 v15, v77, v29
	v_fmac_f32_e32 v15, v78, v30
	v_fmac_f32_e32 v15, v79, v31
	v_fmac_f32_e32 v15, v80, v32
	v_fmac_f32_e32 v15, v81, v33
	v_fmac_f32_e32 v15, v82, v34
	v_fmac_f32_e32 v15, v83, v35
	v_fmac_f32_e32 v15, v84, v36
	v_fmac_f32_e32 v15, v85, v37
	v_fmac_f32_e32 v15, v86, v38
	v_fmac_f32_e32 v15, v87, v39
	v_fmac_f32_e32 v15, v88, v40
	v_fmac_f32_e32 v15, v89, v41
	ds_read_b128 v[74:77], v20 offset:20480
	ds_read_b128 v[78:81], v20 offset:20496
	ds_read_b128 v[82:85], v20 offset:20512
	ds_read_b128 v[86:89], v20 offset:20528
	s_waitcnt lgkmcnt(4)
	v_fmac_f32_e32 v16, v58, v26
	v_fmac_f32_e32 v16, v59, v27
	v_fmac_f32_e32 v16, v60, v28
	v_fmac_f32_e32 v16, v61, v29
	v_fmac_f32_e32 v16, v62, v30
	v_fmac_f32_e32 v16, v63, v31
	v_fmac_f32_e32 v16, v64, v32
	v_fmac_f32_e32 v16, v65, v33
	v_fmac_f32_e32 v16, v66, v34
	v_fmac_f32_e32 v16, v67, v35
	v_fmac_f32_e32 v16, v68, v36
	v_fmac_f32_e32 v16, v69, v37
	v_fmac_f32_e32 v16, v70, v38
	v_fmac_f32_e32 v16, v71, v39
	v_fmac_f32_e32 v16, v72, v40
	v_fmac_f32_e32 v16, v73, v41
	ds_read_b128 v[58:61], v20 offset:24576
	ds_read_b128 v[62:65], v20 offset:24592
	ds_read_b128 v[66:69], v20 offset:24608
	ds_read_b128 v[70:73], v20 offset:24624
	s_waitcnt lgkmcnt(4)
	v_fmac_f32_e32 v17, v74, v26
	v_fmac_f32_e32 v17, v75, v27
	v_fmac_f32_e32 v17, v76, v28
	v_fmac_f32_e32 v17, v77, v29
	v_fmac_f32_e32 v17, v78, v30
	v_fmac_f32_e32 v17, v79, v31
	v_fmac_f32_e32 v17, v80, v32
	v_fmac_f32_e32 v17, v81, v33
	v_fmac_f32_e32 v17, v82, v34
	v_fmac_f32_e32 v17, v83, v35
	v_fmac_f32_e32 v17, v84, v36
	v_fmac_f32_e32 v17, v85, v37
	v_fmac_f32_e32 v17, v86, v38
	v_fmac_f32_e32 v17, v87, v39
	v_fmac_f32_e32 v17, v88, v40
	v_fmac_f32_e32 v17, v89, v41
	ds_read_b128 v[74:77], v20 offset:28672
	ds_read_b128 v[78:81], v20 offset:28688
	ds_read_b128 v[82:85], v20 offset:28704
	ds_read_b128 v[86:89], v20 offset:28720
	s_waitcnt lgkmcnt(4)
	v_fmac_f32_e32 v10, v58, v26
	v_fmac_f32_e32 v10, v59, v27
	v_fmac_f32_e32 v10, v60, v28
	v_fmac_f32_e32 v10, v61, v29
	v_fmac_f32_e32 v10, v62, v30
	v_fmac_f32_e32 v10, v63, v31
	v_fmac_f32_e32 v10, v64, v32
	v_fmac_f32_e32 v10, v65, v33
	v_fmac_f32_e32 v10, v66, v34
	v_fmac_f32_e32 v10, v67, v35
	v_fmac_f32_e32 v10, v68, v36
	v_fmac_f32_e32 v10, v69, v37
	v_fmac_f32_e32 v10, v70, v38
	v_fmac_f32_e32 v10, v71, v39
	v_fmac_f32_e32 v10, v72, v40
	v_fmac_f32_e32 v10, v73, v41
	s_waitcnt lgkmcnt(0)
	v_fmac_f32_e32 v11, v74, v26
	v_fmac_f32_e32 v11, v75, v27
	v_fmac_f32_e32 v11, v76, v28
	v_fmac_f32_e32 v11, v77, v29
	v_fmac_f32_e32 v11, v78, v30
	v_fmac_f32_e32 v11, v79, v31
	v_fmac_f32_e32 v11, v80, v32
	v_fmac_f32_e32 v11, v81, v33
	v_fmac_f32_e32 v11, v82, v34
	v_fmac_f32_e32 v11, v83, v35
	v_fmac_f32_e32 v11, v84, v36
	v_fmac_f32_e32 v11, v85, v37
	v_fmac_f32_e32 v11, v86, v38
	v_fmac_f32_e32 v11, v87, v39
	v_fmac_f32_e32 v11, v88, v40
	v_fmac_f32_e32 v11, v89, v41
	v_mov_b32_e32 v20, s33
	s_add_i32 s33, s33, 64
	ds_read_b128 v[58:61], v20 offset:0
	ds_read_b128 v[62:65], v20 offset:16
	ds_read_b128 v[66:69], v20 offset:32
	ds_read_b128 v[70:73], v20 offset:48
	global_load_dword v26, v[18:19], off
	v_lshl_add_u64 v[18:19], v[18:19], 0, s[34:35]
	global_load_dword v27, v[18:19], off
	v_lshl_add_u64 v[18:19], v[18:19], 0, s[34:35]
	global_load_dword v28, v[18:19], off
	v_lshl_add_u64 v[18:19], v[18:19], 0, s[34:35]
	global_load_dword v29, v[18:19], off
	v_lshl_add_u64 v[18:19], v[18:19], 0, s[34:35]
	global_load_dword v30, v[18:19], off
	v_lshl_add_u64 v[18:19], v[18:19], 0, s[34:35]
	global_load_dword v31, v[18:19], off
	v_lshl_add_u64 v[18:19], v[18:19], 0, s[34:35]
	global_load_dword v32, v[18:19], off
	v_lshl_add_u64 v[18:19], v[18:19], 0, s[34:35]
	global_load_dword v33, v[18:19], off
	v_lshl_add_u64 v[18:19], v[18:19], 0, s[34:35]
	global_load_dword v34, v[18:19], off
	v_lshl_add_u64 v[18:19], v[18:19], 0, s[34:35]
	global_load_dword v35, v[18:19], off
	v_lshl_add_u64 v[18:19], v[18:19], 0, s[34:35]
	global_load_dword v36, v[18:19], off
	v_lshl_add_u64 v[18:19], v[18:19], 0, s[34:35]
	global_load_dword v37, v[18:19], off
	v_lshl_add_u64 v[18:19], v[18:19], 0, s[34:35]
	global_load_dword v38, v[18:19], off
	v_lshl_add_u64 v[18:19], v[18:19], 0, s[34:35]
	global_load_dword v39, v[18:19], off
	v_lshl_add_u64 v[18:19], v[18:19], 0, s[34:35]
	global_load_dword v40, v[18:19], off
	v_lshl_add_u64 v[18:19], v[18:19], 0, s[34:35]
	global_load_dword v41, v[18:19], off
	v_lshl_add_u64 v[18:19], v[18:19], 0, s[34:35]
	s_waitcnt vmcnt(16)
	ds_read_b128 v[74:77], v20 offset:4096
	ds_read_b128 v[78:81], v20 offset:4112
	ds_read_b128 v[82:85], v20 offset:4128
	ds_read_b128 v[86:89], v20 offset:4144
	s_waitcnt lgkmcnt(4)
	v_fmac_f32_e32 v12, v58, v42
	v_fmac_f32_e32 v12, v59, v43
	v_fmac_f32_e32 v12, v60, v44
	v_fmac_f32_e32 v12, v61, v45
	v_fmac_f32_e32 v12, v62, v46
	v_fmac_f32_e32 v12, v63, v47
	v_fmac_f32_e32 v12, v64, v48
	v_fmac_f32_e32 v12, v65, v49
	v_fmac_f32_e32 v12, v66, v50
	v_fmac_f32_e32 v12, v67, v51
	v_fmac_f32_e32 v12, v68, v52
	v_fmac_f32_e32 v12, v69, v53
	v_fmac_f32_e32 v12, v70, v54
	v_fmac_f32_e32 v12, v71, v55
	v_fmac_f32_e32 v12, v72, v56
	v_fmac_f32_e32 v12, v73, v57
	ds_read_b128 v[58:61], v20 offset:8192
	ds_read_b128 v[62:65], v20 offset:8208
	ds_read_b128 v[66:69], v20 offset:8224
	ds_read_b128 v[70:73], v20 offset:8240
	s_waitcnt lgkmcnt(4)
	v_fmac_f32_e32 v13, v74, v42
	v_fmac_f32_e32 v13, v75, v43
	v_fmac_f32_e32 v13, v76, v44
	v_fmac_f32_e32 v13, v77, v45
	v_fmac_f32_e32 v13, v78, v46
	v_fmac_f32_e32 v13, v79, v47
	v_fmac_f32_e32 v13, v80, v48
	v_fmac_f32_e32 v13, v81, v49
	v_fmac_f32_e32 v13, v82, v50
	v_fmac_f32_e32 v13, v83, v51
	v_fmac_f32_e32 v13, v84, v52
	v_fmac_f32_e32 v13, v85, v53
	v_fmac_f32_e32 v13, v86, v54
	v_fmac_f32_e32 v13, v87, v55
	v_fmac_f32_e32 v13, v88, v56
	v_fmac_f32_e32 v13, v89, v57
	ds_read_b128 v[74:77], v20 offset:12288
	ds_read_b128 v[78:81], v20 offset:12304
	ds_read_b128 v[82:85], v20 offset:12320
	ds_read_b128 v[86:89], v20 offset:12336
	s_waitcnt lgkmcnt(4)
	v_fmac_f32_e32 v14, v58, v42
	v_fmac_f32_e32 v14, v59, v43
	v_fmac_f32_e32 v14, v60, v44
	v_fmac_f32_e32 v14, v61, v45
	v_fmac_f32_e32 v14, v62, v46
	v_fmac_f32_e32 v14, v63, v47
	v_fmac_f32_e32 v14, v64, v48
	v_fmac_f32_e32 v14, v65, v49
	v_fmac_f32_e32 v14, v66, v50
	v_fmac_f32_e32 v14, v67, v51
	v_fmac_f32_e32 v14, v68, v52
	v_fmac_f32_e32 v14, v69, v53
	v_fmac_f32_e32 v14, v70, v54
	v_fmac_f32_e32 v14, v71, v55
	v_fmac_f32_e32 v14, v72, v56
	v_fmac_f32_e32 v14, v73, v57
	ds_read_b128 v[58:61], v20 offset:16384
	ds_read_b128 v[62:65], v20 offset:16400
	ds_read_b128 v[66:69], v20 offset:16416
	ds_read_b128 v[70:73], v20 offset:16432
	s_waitcnt lgkmcnt(4)
	v_fmac_f32_e32 v15, v74, v42
	v_fmac_f32_e32 v15, v75, v43
	v_fmac_f32_e32 v15, v76, v44
	v_fmac_f32_e32 v15, v77, v45
	v_fmac_f32_e32 v15, v78, v46
	v_fmac_f32_e32 v15, v79, v47
	v_fmac_f32_e32 v15, v80, v48
	v_fmac_f32_e32 v15, v81, v49
	v_fmac_f32_e32 v15, v82, v50
	v_fmac_f32_e32 v15, v83, v51
	v_fmac_f32_e32 v15, v84, v52
	v_fmac_f32_e32 v15, v85, v53
	v_fmac_f32_e32 v15, v86, v54
	v_fmac_f32_e32 v15, v87, v55
	v_fmac_f32_e32 v15, v88, v56
	v_fmac_f32_e32 v15, v89, v57
	ds_read_b128 v[74:77], v20 offset:20480
	ds_read_b128 v[78:81], v20 offset:20496
	ds_read_b128 v[82:85], v20 offset:20512
	ds_read_b128 v[86:89], v20 offset:20528
	s_waitcnt lgkmcnt(4)
	v_fmac_f32_e32 v16, v58, v42
	v_fmac_f32_e32 v16, v59, v43
	v_fmac_f32_e32 v16, v60, v44
	v_fmac_f32_e32 v16, v61, v45
	v_fmac_f32_e32 v16, v62, v46
	v_fmac_f32_e32 v16, v63, v47
	v_fmac_f32_e32 v16, v64, v48
	v_fmac_f32_e32 v16, v65, v49
	v_fmac_f32_e32 v16, v66, v50
	v_fmac_f32_e32 v16, v67, v51
	v_fmac_f32_e32 v16, v68, v52
	v_fmac_f32_e32 v16, v69, v53
	v_fmac_f32_e32 v16, v70, v54
	v_fmac_f32_e32 v16, v71, v55
	v_fmac_f32_e32 v16, v72, v56
	v_fmac_f32_e32 v16, v73, v57
	ds_read_b128 v[58:61], v20 offset:24576
	ds_read_b128 v[62:65], v20 offset:24592
	ds_read_b128 v[66:69], v20 offset:24608
	ds_read_b128 v[70:73], v20 offset:24624
	s_waitcnt lgkmcnt(4)
	v_fmac_f32_e32 v17, v74, v42
	v_fmac_f32_e32 v17, v75, v43
	v_fmac_f32_e32 v17, v76, v44
	v_fmac_f32_e32 v17, v77, v45
	v_fmac_f32_e32 v17, v78, v46
	v_fmac_f32_e32 v17, v79, v47
	v_fmac_f32_e32 v17, v80, v48
	v_fmac_f32_e32 v17, v81, v49
	v_fmac_f32_e32 v17, v82, v50
	v_fmac_f32_e32 v17, v83, v51
	v_fmac_f32_e32 v17, v84, v52
	v_fmac_f32_e32 v17, v85, v53
	v_fmac_f32_e32 v17, v86, v54
	v_fmac_f32_e32 v17, v87, v55
	v_fmac_f32_e32 v17, v88, v56
	v_fmac_f32_e32 v17, v89, v57
	ds_read_b128 v[74:77], v20 offset:28672
	ds_read_b128 v[78:81], v20 offset:28688
	ds_read_b128 v[82:85], v20 offset:28704
	ds_read_b128 v[86:89], v20 offset:28720
	s_waitcnt lgkmcnt(4)
	v_fmac_f32_e32 v10, v58, v42
	v_fmac_f32_e32 v10, v59, v43
	v_fmac_f32_e32 v10, v60, v44
	v_fmac_f32_e32 v10, v61, v45
	v_fmac_f32_e32 v10, v62, v46
	v_fmac_f32_e32 v10, v63, v47
	v_fmac_f32_e32 v10, v64, v48
	v_fmac_f32_e32 v10, v65, v49
	v_fmac_f32_e32 v10, v66, v50
	v_fmac_f32_e32 v10, v67, v51
	v_fmac_f32_e32 v10, v68, v52
	v_fmac_f32_e32 v10, v69, v53
	v_fmac_f32_e32 v10, v70, v54
	v_fmac_f32_e32 v10, v71, v55
	v_fmac_f32_e32 v10, v72, v56
	v_fmac_f32_e32 v10, v73, v57
	s_waitcnt lgkmcnt(0)
	v_fmac_f32_e32 v11, v74, v42
	v_fmac_f32_e32 v11, v75, v43
	v_fmac_f32_e32 v11, v76, v44
	v_fmac_f32_e32 v11, v77, v45
	v_fmac_f32_e32 v11, v78, v46
	v_fmac_f32_e32 v11, v79, v47
	v_fmac_f32_e32 v11, v80, v48
	v_fmac_f32_e32 v11, v81, v49
	v_fmac_f32_e32 v11, v82, v50
	v_fmac_f32_e32 v11, v83, v51
	v_fmac_f32_e32 v11, v84, v52
	v_fmac_f32_e32 v11, v85, v53
	v_fmac_f32_e32 v11, v86, v54
	v_fmac_f32_e32 v11, v87, v55
	v_fmac_f32_e32 v11, v88, v56
	v_fmac_f32_e32 v11, v89, v57
	v_mov_b32_e32 v20, s33
	s_add_i32 s33, s33, 64
	ds_read_b128 v[58:61], v20 offset:0
	ds_read_b128 v[62:65], v20 offset:16
	ds_read_b128 v[66:69], v20 offset:32
	ds_read_b128 v[70:73], v20 offset:48
	global_load_dword v42, v[18:19], off
	v_lshl_add_u64 v[18:19], v[18:19], 0, s[34:35]
	global_load_dword v43, v[18:19], off
	v_lshl_add_u64 v[18:19], v[18:19], 0, s[34:35]
	global_load_dword v44, v[18:19], off
	v_lshl_add_u64 v[18:19], v[18:19], 0, s[34:35]
	global_load_dword v45, v[18:19], off
	v_lshl_add_u64 v[18:19], v[18:19], 0, s[34:35]
	global_load_dword v46, v[18:19], off
	v_lshl_add_u64 v[18:19], v[18:19], 0, s[34:35]
	global_load_dword v47, v[18:19], off
	v_lshl_add_u64 v[18:19], v[18:19], 0, s[34:35]
	global_load_dword v48, v[18:19], off
	v_lshl_add_u64 v[18:19], v[18:19], 0, s[34:35]
	global_load_dword v49, v[18:19], off
	v_lshl_add_u64 v[18:19], v[18:19], 0, s[34:35]
	global_load_dword v50, v[18:19], off
	v_lshl_add_u64 v[18:19], v[18:19], 0, s[34:35]
	global_load_dword v51, v[18:19], off
	v_lshl_add_u64 v[18:19], v[18:19], 0, s[34:35]
	global_load_dword v52, v[18:19], off
	v_lshl_add_u64 v[18:19], v[18:19], 0, s[34:35]
	global_load_dword v53, v[18:19], off
	v_lshl_add_u64 v[18:19], v[18:19], 0, s[34:35]
	global_load_dword v54, v[18:19], off
	v_lshl_add_u64 v[18:19], v[18:19], 0, s[34:35]
	global_load_dword v55, v[18:19], off
	v_lshl_add_u64 v[18:19], v[18:19], 0, s[34:35]
	global_load_dword v56, v[18:19], off
	v_lshl_add_u64 v[18:19], v[18:19], 0, s[34:35]
	global_load_dword v57, v[18:19], off
	v_lshl_add_u64 v[18:19], v[18:19], 0, s[34:35]
	s_waitcnt vmcnt(16)
	ds_read_b128 v[74:77], v20 offset:4096
	ds_read_b128 v[78:81], v20 offset:4112
	ds_read_b128 v[82:85], v20 offset:4128
	ds_read_b128 v[86:89], v20 offset:4144
	s_waitcnt lgkmcnt(4)
	v_fmac_f32_e32 v12, v58, v26
	v_fmac_f32_e32 v12, v59, v27
	v_fmac_f32_e32 v12, v60, v28
	v_fmac_f32_e32 v12, v61, v29
	v_fmac_f32_e32 v12, v62, v30
	v_fmac_f32_e32 v12, v63, v31
	v_fmac_f32_e32 v12, v64, v32
	v_fmac_f32_e32 v12, v65, v33
	v_fmac_f32_e32 v12, v66, v34
	v_fmac_f32_e32 v12, v67, v35
	v_fmac_f32_e32 v12, v68, v36
	v_fmac_f32_e32 v12, v69, v37
	v_fmac_f32_e32 v12, v70, v38
	v_fmac_f32_e32 v12, v71, v39
	v_fmac_f32_e32 v12, v72, v40
	v_fmac_f32_e32 v12, v73, v41
	ds_read_b128 v[58:61], v20 offset:8192
	ds_read_b128 v[62:65], v20 offset:8208
	ds_read_b128 v[66:69], v20 offset:8224
	ds_read_b128 v[70:73], v20 offset:8240
	s_waitcnt lgkmcnt(4)
	v_fmac_f32_e32 v13, v74, v26
	v_fmac_f32_e32 v13, v75, v27
	v_fmac_f32_e32 v13, v76, v28
	v_fmac_f32_e32 v13, v77, v29
	v_fmac_f32_e32 v13, v78, v30
	v_fmac_f32_e32 v13, v79, v31
	v_fmac_f32_e32 v13, v80, v32
	v_fmac_f32_e32 v13, v81, v33
	v_fmac_f32_e32 v13, v82, v34
	v_fmac_f32_e32 v13, v83, v35
	v_fmac_f32_e32 v13, v84, v36
	v_fmac_f32_e32 v13, v85, v37
	v_fmac_f32_e32 v13, v86, v38
	v_fmac_f32_e32 v13, v87, v39
	v_fmac_f32_e32 v13, v88, v40
	v_fmac_f32_e32 v13, v89, v41
	ds_read_b128 v[74:77], v20 offset:12288
	ds_read_b128 v[78:81], v20 offset:12304
	ds_read_b128 v[82:85], v20 offset:12320
	ds_read_b128 v[86:89], v20 offset:12336
	s_waitcnt lgkmcnt(4)
	v_fmac_f32_e32 v14, v58, v26
	v_fmac_f32_e32 v14, v59, v27
	v_fmac_f32_e32 v14, v60, v28
	v_fmac_f32_e32 v14, v61, v29
	v_fmac_f32_e32 v14, v62, v30
	v_fmac_f32_e32 v14, v63, v31
	v_fmac_f32_e32 v14, v64, v32
	v_fmac_f32_e32 v14, v65, v33
	v_fmac_f32_e32 v14, v66, v34
	v_fmac_f32_e32 v14, v67, v35
	v_fmac_f32_e32 v14, v68, v36
	v_fmac_f32_e32 v14, v69, v37
	v_fmac_f32_e32 v14, v70, v38
	v_fmac_f32_e32 v14, v71, v39
	v_fmac_f32_e32 v14, v72, v40
	v_fmac_f32_e32 v14, v73, v41
	ds_read_b128 v[58:61], v20 offset:16384
	ds_read_b128 v[62:65], v20 offset:16400
	ds_read_b128 v[66:69], v20 offset:16416
	ds_read_b128 v[70:73], v20 offset:16432
	s_waitcnt lgkmcnt(4)
	v_fmac_f32_e32 v15, v74, v26
	v_fmac_f32_e32 v15, v75, v27
	v_fmac_f32_e32 v15, v76, v28
	v_fmac_f32_e32 v15, v77, v29
	v_fmac_f32_e32 v15, v78, v30
	v_fmac_f32_e32 v15, v79, v31
	v_fmac_f32_e32 v15, v80, v32
	v_fmac_f32_e32 v15, v81, v33
	v_fmac_f32_e32 v15, v82, v34
	v_fmac_f32_e32 v15, v83, v35
	v_fmac_f32_e32 v15, v84, v36
	v_fmac_f32_e32 v15, v85, v37
	v_fmac_f32_e32 v15, v86, v38
	v_fmac_f32_e32 v15, v87, v39
	v_fmac_f32_e32 v15, v88, v40
	v_fmac_f32_e32 v15, v89, v41
	ds_read_b128 v[74:77], v20 offset:20480
	ds_read_b128 v[78:81], v20 offset:20496
	ds_read_b128 v[82:85], v20 offset:20512
	ds_read_b128 v[86:89], v20 offset:20528
	s_waitcnt lgkmcnt(4)
	v_fmac_f32_e32 v16, v58, v26
	v_fmac_f32_e32 v16, v59, v27
	v_fmac_f32_e32 v16, v60, v28
	v_fmac_f32_e32 v16, v61, v29
	v_fmac_f32_e32 v16, v62, v30
	v_fmac_f32_e32 v16, v63, v31
	v_fmac_f32_e32 v16, v64, v32
	v_fmac_f32_e32 v16, v65, v33
	v_fmac_f32_e32 v16, v66, v34
	v_fmac_f32_e32 v16, v67, v35
	v_fmac_f32_e32 v16, v68, v36
	v_fmac_f32_e32 v16, v69, v37
	v_fmac_f32_e32 v16, v70, v38
	v_fmac_f32_e32 v16, v71, v39
	v_fmac_f32_e32 v16, v72, v40
	v_fmac_f32_e32 v16, v73, v41
	ds_read_b128 v[58:61], v20 offset:24576
	ds_read_b128 v[62:65], v20 offset:24592
	ds_read_b128 v[66:69], v20 offset:24608
	ds_read_b128 v[70:73], v20 offset:24624
	s_waitcnt lgkmcnt(4)
	v_fmac_f32_e32 v17, v74, v26
	v_fmac_f32_e32 v17, v75, v27
	v_fmac_f32_e32 v17, v76, v28
	v_fmac_f32_e32 v17, v77, v29
	v_fmac_f32_e32 v17, v78, v30
	v_fmac_f32_e32 v17, v79, v31
	v_fmac_f32_e32 v17, v80, v32
	v_fmac_f32_e32 v17, v81, v33
	v_fmac_f32_e32 v17, v82, v34
	v_fmac_f32_e32 v17, v83, v35
	v_fmac_f32_e32 v17, v84, v36
	v_fmac_f32_e32 v17, v85, v37
	v_fmac_f32_e32 v17, v86, v38
	v_fmac_f32_e32 v17, v87, v39
	v_fmac_f32_e32 v17, v88, v40
	v_fmac_f32_e32 v17, v89, v41
	ds_read_b128 v[74:77], v20 offset:28672
	ds_read_b128 v[78:81], v20 offset:28688
	ds_read_b128 v[82:85], v20 offset:28704
	ds_read_b128 v[86:89], v20 offset:28720
	s_waitcnt lgkmcnt(4)
	v_fmac_f32_e32 v10, v58, v26
	v_fmac_f32_e32 v10, v59, v27
	v_fmac_f32_e32 v10, v60, v28
	v_fmac_f32_e32 v10, v61, v29
	v_fmac_f32_e32 v10, v62, v30
	v_fmac_f32_e32 v10, v63, v31
	v_fmac_f32_e32 v10, v64, v32
	v_fmac_f32_e32 v10, v65, v33
	v_fmac_f32_e32 v10, v66, v34
	v_fmac_f32_e32 v10, v67, v35
	v_fmac_f32_e32 v10, v68, v36
	v_fmac_f32_e32 v10, v69, v37
	v_fmac_f32_e32 v10, v70, v38
	v_fmac_f32_e32 v10, v71, v39
	v_fmac_f32_e32 v10, v72, v40
	v_fmac_f32_e32 v10, v73, v41
	s_waitcnt lgkmcnt(0)
	v_fmac_f32_e32 v11, v74, v26
	v_fmac_f32_e32 v11, v75, v27
	v_fmac_f32_e32 v11, v76, v28
	v_fmac_f32_e32 v11, v77, v29
	v_fmac_f32_e32 v11, v78, v30
	v_fmac_f32_e32 v11, v79, v31
	v_fmac_f32_e32 v11, v80, v32
	v_fmac_f32_e32 v11, v81, v33
	v_fmac_f32_e32 v11, v82, v34
	v_fmac_f32_e32 v11, v83, v35
	v_fmac_f32_e32 v11, v84, v36
	v_fmac_f32_e32 v11, v85, v37
	v_fmac_f32_e32 v11, v86, v38
	v_fmac_f32_e32 v11, v87, v39
	v_fmac_f32_e32 v11, v88, v40
	v_fmac_f32_e32 v11, v89, v41
	v_mov_b32_e32 v20, s33
	s_add_i32 s33, s33, 64
	ds_read_b128 v[58:61], v20 offset:0
	ds_read_b128 v[62:65], v20 offset:16
	ds_read_b128 v[66:69], v20 offset:32
	ds_read_b128 v[70:73], v20 offset:48
	global_load_dword v26, v[18:19], off
	v_lshl_add_u64 v[18:19], v[18:19], 0, s[34:35]
	global_load_dword v27, v[18:19], off
	v_lshl_add_u64 v[18:19], v[18:19], 0, s[34:35]
	global_load_dword v28, v[18:19], off
	v_lshl_add_u64 v[18:19], v[18:19], 0, s[34:35]
	global_load_dword v29, v[18:19], off
	v_lshl_add_u64 v[18:19], v[18:19], 0, s[34:35]
	global_load_dword v30, v[18:19], off
	v_lshl_add_u64 v[18:19], v[18:19], 0, s[34:35]
	global_load_dword v31, v[18:19], off
	v_lshl_add_u64 v[18:19], v[18:19], 0, s[34:35]
	global_load_dword v32, v[18:19], off
	v_lshl_add_u64 v[18:19], v[18:19], 0, s[34:35]
	global_load_dword v33, v[18:19], off
	v_lshl_add_u64 v[18:19], v[18:19], 0, s[34:35]
	global_load_dword v34, v[18:19], off
	v_lshl_add_u64 v[18:19], v[18:19], 0, s[34:35]
	global_load_dword v35, v[18:19], off
	v_lshl_add_u64 v[18:19], v[18:19], 0, s[34:35]
	global_load_dword v36, v[18:19], off
	v_lshl_add_u64 v[18:19], v[18:19], 0, s[34:35]
	global_load_dword v37, v[18:19], off
	v_lshl_add_u64 v[18:19], v[18:19], 0, s[34:35]
	global_load_dword v38, v[18:19], off
	v_lshl_add_u64 v[18:19], v[18:19], 0, s[34:35]
	global_load_dword v39, v[18:19], off
	v_lshl_add_u64 v[18:19], v[18:19], 0, s[34:35]
	global_load_dword v40, v[18:19], off
	v_lshl_add_u64 v[18:19], v[18:19], 0, s[34:35]
	global_load_dword v41, v[18:19], off
	v_lshl_add_u64 v[18:19], v[18:19], 0, s[34:35]
	s_waitcnt vmcnt(16)
	ds_read_b128 v[74:77], v20 offset:4096
	ds_read_b128 v[78:81], v20 offset:4112
	ds_read_b128 v[82:85], v20 offset:4128
	ds_read_b128 v[86:89], v20 offset:4144
	s_waitcnt lgkmcnt(4)
	v_fmac_f32_e32 v12, v58, v42
	v_fmac_f32_e32 v12, v59, v43
	v_fmac_f32_e32 v12, v60, v44
	v_fmac_f32_e32 v12, v61, v45
	v_fmac_f32_e32 v12, v62, v46
	v_fmac_f32_e32 v12, v63, v47
	v_fmac_f32_e32 v12, v64, v48
	v_fmac_f32_e32 v12, v65, v49
	v_fmac_f32_e32 v12, v66, v50
	v_fmac_f32_e32 v12, v67, v51
	v_fmac_f32_e32 v12, v68, v52
	v_fmac_f32_e32 v12, v69, v53
	v_fmac_f32_e32 v12, v70, v54
	v_fmac_f32_e32 v12, v71, v55
	v_fmac_f32_e32 v12, v72, v56
	v_fmac_f32_e32 v12, v73, v57
	ds_read_b128 v[58:61], v20 offset:8192
	ds_read_b128 v[62:65], v20 offset:8208
	ds_read_b128 v[66:69], v20 offset:8224
	ds_read_b128 v[70:73], v20 offset:8240
	s_waitcnt lgkmcnt(4)
	v_fmac_f32_e32 v13, v74, v42
	v_fmac_f32_e32 v13, v75, v43
	v_fmac_f32_e32 v13, v76, v44
	v_fmac_f32_e32 v13, v77, v45
	v_fmac_f32_e32 v13, v78, v46
	v_fmac_f32_e32 v13, v79, v47
	v_fmac_f32_e32 v13, v80, v48
	v_fmac_f32_e32 v13, v81, v49
	v_fmac_f32_e32 v13, v82, v50
	v_fmac_f32_e32 v13, v83, v51
	v_fmac_f32_e32 v13, v84, v52
	v_fmac_f32_e32 v13, v85, v53
	v_fmac_f32_e32 v13, v86, v54
	v_fmac_f32_e32 v13, v87, v55
	v_fmac_f32_e32 v13, v88, v56
	v_fmac_f32_e32 v13, v89, v57
	ds_read_b128 v[74:77], v20 offset:12288
	ds_read_b128 v[78:81], v20 offset:12304
	ds_read_b128 v[82:85], v20 offset:12320
	ds_read_b128 v[86:89], v20 offset:12336
	s_waitcnt lgkmcnt(4)
	v_fmac_f32_e32 v14, v58, v42
	v_fmac_f32_e32 v14, v59, v43
	v_fmac_f32_e32 v14, v60, v44
	v_fmac_f32_e32 v14, v61, v45
	v_fmac_f32_e32 v14, v62, v46
	v_fmac_f32_e32 v14, v63, v47
	v_fmac_f32_e32 v14, v64, v48
	v_fmac_f32_e32 v14, v65, v49
	v_fmac_f32_e32 v14, v66, v50
	v_fmac_f32_e32 v14, v67, v51
	v_fmac_f32_e32 v14, v68, v52
	v_fmac_f32_e32 v14, v69, v53
	v_fmac_f32_e32 v14, v70, v54
	v_fmac_f32_e32 v14, v71, v55
	v_fmac_f32_e32 v14, v72, v56
	v_fmac_f32_e32 v14, v73, v57
	ds_read_b128 v[58:61], v20 offset:16384
	ds_read_b128 v[62:65], v20 offset:16400
	ds_read_b128 v[66:69], v20 offset:16416
	ds_read_b128 v[70:73], v20 offset:16432
	s_waitcnt lgkmcnt(4)
	v_fmac_f32_e32 v15, v74, v42
	v_fmac_f32_e32 v15, v75, v43
	v_fmac_f32_e32 v15, v76, v44
	v_fmac_f32_e32 v15, v77, v45
	v_fmac_f32_e32 v15, v78, v46
	v_fmac_f32_e32 v15, v79, v47
	v_fmac_f32_e32 v15, v80, v48
	v_fmac_f32_e32 v15, v81, v49
	v_fmac_f32_e32 v15, v82, v50
	v_fmac_f32_e32 v15, v83, v51
	v_fmac_f32_e32 v15, v84, v52
	v_fmac_f32_e32 v15, v85, v53
	v_fmac_f32_e32 v15, v86, v54
	v_fmac_f32_e32 v15, v87, v55
	v_fmac_f32_e32 v15, v88, v56
	v_fmac_f32_e32 v15, v89, v57
	ds_read_b128 v[74:77], v20 offset:20480
	ds_read_b128 v[78:81], v20 offset:20496
	ds_read_b128 v[82:85], v20 offset:20512
	ds_read_b128 v[86:89], v20 offset:20528
	s_waitcnt lgkmcnt(4)
	v_fmac_f32_e32 v16, v58, v42
	v_fmac_f32_e32 v16, v59, v43
	v_fmac_f32_e32 v16, v60, v44
	v_fmac_f32_e32 v16, v61, v45
	v_fmac_f32_e32 v16, v62, v46
	v_fmac_f32_e32 v16, v63, v47
	v_fmac_f32_e32 v16, v64, v48
	v_fmac_f32_e32 v16, v65, v49
	v_fmac_f32_e32 v16, v66, v50
	v_fmac_f32_e32 v16, v67, v51
	v_fmac_f32_e32 v16, v68, v52
	v_fmac_f32_e32 v16, v69, v53
	v_fmac_f32_e32 v16, v70, v54
	v_fmac_f32_e32 v16, v71, v55
	v_fmac_f32_e32 v16, v72, v56
	v_fmac_f32_e32 v16, v73, v57
	ds_read_b128 v[58:61], v20 offset:24576
	ds_read_b128 v[62:65], v20 offset:24592
	ds_read_b128 v[66:69], v20 offset:24608
	ds_read_b128 v[70:73], v20 offset:24624
	s_waitcnt lgkmcnt(4)
	v_fmac_f32_e32 v17, v74, v42
	v_fmac_f32_e32 v17, v75, v43
	v_fmac_f32_e32 v17, v76, v44
	v_fmac_f32_e32 v17, v77, v45
	v_fmac_f32_e32 v17, v78, v46
	v_fmac_f32_e32 v17, v79, v47
	v_fmac_f32_e32 v17, v80, v48
	v_fmac_f32_e32 v17, v81, v49
	v_fmac_f32_e32 v17, v82, v50
	v_fmac_f32_e32 v17, v83, v51
	v_fmac_f32_e32 v17, v84, v52
	v_fmac_f32_e32 v17, v85, v53
	v_fmac_f32_e32 v17, v86, v54
	v_fmac_f32_e32 v17, v87, v55
	v_fmac_f32_e32 v17, v88, v56
	v_fmac_f32_e32 v17, v89, v57
	ds_read_b128 v[74:77], v20 offset:28672
	ds_read_b128 v[78:81], v20 offset:28688
	ds_read_b128 v[82:85], v20 offset:28704
	ds_read_b128 v[86:89], v20 offset:28720
	s_waitcnt lgkmcnt(4)
	v_fmac_f32_e32 v10, v58, v42
	v_fmac_f32_e32 v10, v59, v43
	v_fmac_f32_e32 v10, v60, v44
	v_fmac_f32_e32 v10, v61, v45
	v_fmac_f32_e32 v10, v62, v46
	v_fmac_f32_e32 v10, v63, v47
	v_fmac_f32_e32 v10, v64, v48
	v_fmac_f32_e32 v10, v65, v49
	v_fmac_f32_e32 v10, v66, v50
	v_fmac_f32_e32 v10, v67, v51
	v_fmac_f32_e32 v10, v68, v52
	v_fmac_f32_e32 v10, v69, v53
	v_fmac_f32_e32 v10, v70, v54
	v_fmac_f32_e32 v10, v71, v55
	v_fmac_f32_e32 v10, v72, v56
	v_fmac_f32_e32 v10, v73, v57
	s_waitcnt lgkmcnt(0)
	v_fmac_f32_e32 v11, v74, v42
	v_fmac_f32_e32 v11, v75, v43
	v_fmac_f32_e32 v11, v76, v44
	v_fmac_f32_e32 v11, v77, v45
	v_fmac_f32_e32 v11, v78, v46
	v_fmac_f32_e32 v11, v79, v47
	v_fmac_f32_e32 v11, v80, v48
	v_fmac_f32_e32 v11, v81, v49
	v_fmac_f32_e32 v11, v82, v50
	v_fmac_f32_e32 v11, v83, v51
	v_fmac_f32_e32 v11, v84, v52
	v_fmac_f32_e32 v11, v85, v53
	v_fmac_f32_e32 v11, v86, v54
	v_fmac_f32_e32 v11, v87, v55
	v_fmac_f32_e32 v11, v88, v56
	v_fmac_f32_e32 v11, v89, v57
	v_mov_b32_e32 v20, s33
	s_add_i32 s33, s33, 64
	ds_read_b128 v[58:61], v20 offset:0
	ds_read_b128 v[62:65], v20 offset:16
	ds_read_b128 v[66:69], v20 offset:32
	ds_read_b128 v[70:73], v20 offset:48
	global_load_dword v42, v[18:19], off
	v_lshl_add_u64 v[18:19], v[18:19], 0, s[34:35]
	global_load_dword v43, v[18:19], off
	v_lshl_add_u64 v[18:19], v[18:19], 0, s[34:35]
	global_load_dword v44, v[18:19], off
	v_lshl_add_u64 v[18:19], v[18:19], 0, s[34:35]
	global_load_dword v45, v[18:19], off
	v_lshl_add_u64 v[18:19], v[18:19], 0, s[34:35]
	global_load_dword v46, v[18:19], off
	v_lshl_add_u64 v[18:19], v[18:19], 0, s[34:35]
	global_load_dword v47, v[18:19], off
	v_lshl_add_u64 v[18:19], v[18:19], 0, s[34:35]
	global_load_dword v48, v[18:19], off
	v_lshl_add_u64 v[18:19], v[18:19], 0, s[34:35]
	global_load_dword v49, v[18:19], off
	v_lshl_add_u64 v[18:19], v[18:19], 0, s[34:35]
	global_load_dword v50, v[18:19], off
	v_lshl_add_u64 v[18:19], v[18:19], 0, s[34:35]
	global_load_dword v51, v[18:19], off
	v_lshl_add_u64 v[18:19], v[18:19], 0, s[34:35]
	global_load_dword v52, v[18:19], off
	v_lshl_add_u64 v[18:19], v[18:19], 0, s[34:35]
	global_load_dword v53, v[18:19], off
	v_lshl_add_u64 v[18:19], v[18:19], 0, s[34:35]
	global_load_dword v54, v[18:19], off
	v_lshl_add_u64 v[18:19], v[18:19], 0, s[34:35]
	global_load_dword v55, v[18:19], off
	v_lshl_add_u64 v[18:19], v[18:19], 0, s[34:35]
	global_load_dword v56, v[18:19], off
	v_lshl_add_u64 v[18:19], v[18:19], 0, s[34:35]
	global_load_dword v57, v[18:19], off
	v_lshl_add_u64 v[18:19], v[18:19], 0, s[34:35]
	s_waitcnt vmcnt(16)
	ds_read_b128 v[74:77], v20 offset:4096
	ds_read_b128 v[78:81], v20 offset:4112
	ds_read_b128 v[82:85], v20 offset:4128
	ds_read_b128 v[86:89], v20 offset:4144
	s_waitcnt lgkmcnt(4)
	v_fmac_f32_e32 v12, v58, v26
	v_fmac_f32_e32 v12, v59, v27
	v_fmac_f32_e32 v12, v60, v28
	v_fmac_f32_e32 v12, v61, v29
	v_fmac_f32_e32 v12, v62, v30
	v_fmac_f32_e32 v12, v63, v31
	v_fmac_f32_e32 v12, v64, v32
	v_fmac_f32_e32 v12, v65, v33
	v_fmac_f32_e32 v12, v66, v34
	v_fmac_f32_e32 v12, v67, v35
	v_fmac_f32_e32 v12, v68, v36
	v_fmac_f32_e32 v12, v69, v37
	v_fmac_f32_e32 v12, v70, v38
	v_fmac_f32_e32 v12, v71, v39
	v_fmac_f32_e32 v12, v72, v40
	v_fmac_f32_e32 v12, v73, v41
	ds_read_b128 v[58:61], v20 offset:8192
	ds_read_b128 v[62:65], v20 offset:8208
	ds_read_b128 v[66:69], v20 offset:8224
	ds_read_b128 v[70:73], v20 offset:8240
	s_waitcnt lgkmcnt(4)
	v_fmac_f32_e32 v13, v74, v26
	v_fmac_f32_e32 v13, v75, v27
	v_fmac_f32_e32 v13, v76, v28
	v_fmac_f32_e32 v13, v77, v29
	v_fmac_f32_e32 v13, v78, v30
	v_fmac_f32_e32 v13, v79, v31
	v_fmac_f32_e32 v13, v80, v32
	v_fmac_f32_e32 v13, v81, v33
	v_fmac_f32_e32 v13, v82, v34
	v_fmac_f32_e32 v13, v83, v35
	v_fmac_f32_e32 v13, v84, v36
	v_fmac_f32_e32 v13, v85, v37
	v_fmac_f32_e32 v13, v86, v38
	v_fmac_f32_e32 v13, v87, v39
	v_fmac_f32_e32 v13, v88, v40
	v_fmac_f32_e32 v13, v89, v41
	ds_read_b128 v[74:77], v20 offset:12288
	ds_read_b128 v[78:81], v20 offset:12304
	ds_read_b128 v[82:85], v20 offset:12320
	ds_read_b128 v[86:89], v20 offset:12336
	s_waitcnt lgkmcnt(4)
	v_fmac_f32_e32 v14, v58, v26
	v_fmac_f32_e32 v14, v59, v27
	v_fmac_f32_e32 v14, v60, v28
	v_fmac_f32_e32 v14, v61, v29
	v_fmac_f32_e32 v14, v62, v30
	v_fmac_f32_e32 v14, v63, v31
	v_fmac_f32_e32 v14, v64, v32
	v_fmac_f32_e32 v14, v65, v33
	v_fmac_f32_e32 v14, v66, v34
	v_fmac_f32_e32 v14, v67, v35
	v_fmac_f32_e32 v14, v68, v36
	v_fmac_f32_e32 v14, v69, v37
	v_fmac_f32_e32 v14, v70, v38
	v_fmac_f32_e32 v14, v71, v39
	v_fmac_f32_e32 v14, v72, v40
	v_fmac_f32_e32 v14, v73, v41
	ds_read_b128 v[58:61], v20 offset:16384
	ds_read_b128 v[62:65], v20 offset:16400
	ds_read_b128 v[66:69], v20 offset:16416
	ds_read_b128 v[70:73], v20 offset:16432
	s_waitcnt lgkmcnt(4)
	v_fmac_f32_e32 v15, v74, v26
	v_fmac_f32_e32 v15, v75, v27
	v_fmac_f32_e32 v15, v76, v28
	v_fmac_f32_e32 v15, v77, v29
	v_fmac_f32_e32 v15, v78, v30
	v_fmac_f32_e32 v15, v79, v31
	v_fmac_f32_e32 v15, v80, v32
	v_fmac_f32_e32 v15, v81, v33
	v_fmac_f32_e32 v15, v82, v34
	v_fmac_f32_e32 v15, v83, v35
	v_fmac_f32_e32 v15, v84, v36
	v_fmac_f32_e32 v15, v85, v37
	v_fmac_f32_e32 v15, v86, v38
	v_fmac_f32_e32 v15, v87, v39
	v_fmac_f32_e32 v15, v88, v40
	v_fmac_f32_e32 v15, v89, v41
	ds_read_b128 v[74:77], v20 offset:20480
	ds_read_b128 v[78:81], v20 offset:20496
	ds_read_b128 v[82:85], v20 offset:20512
	ds_read_b128 v[86:89], v20 offset:20528
	s_waitcnt lgkmcnt(4)
	v_fmac_f32_e32 v16, v58, v26
	v_fmac_f32_e32 v16, v59, v27
	v_fmac_f32_e32 v16, v60, v28
	v_fmac_f32_e32 v16, v61, v29
	v_fmac_f32_e32 v16, v62, v30
	v_fmac_f32_e32 v16, v63, v31
	v_fmac_f32_e32 v16, v64, v32
	v_fmac_f32_e32 v16, v65, v33
	v_fmac_f32_e32 v16, v66, v34
	v_fmac_f32_e32 v16, v67, v35
	v_fmac_f32_e32 v16, v68, v36
	v_fmac_f32_e32 v16, v69, v37
	v_fmac_f32_e32 v16, v70, v38
	v_fmac_f32_e32 v16, v71, v39
	v_fmac_f32_e32 v16, v72, v40
	v_fmac_f32_e32 v16, v73, v41
	ds_read_b128 v[58:61], v20 offset:24576
	ds_read_b128 v[62:65], v20 offset:24592
	ds_read_b128 v[66:69], v20 offset:24608
	ds_read_b128 v[70:73], v20 offset:24624
	s_waitcnt lgkmcnt(4)
	v_fmac_f32_e32 v17, v74, v26
	v_fmac_f32_e32 v17, v75, v27
	v_fmac_f32_e32 v17, v76, v28
	v_fmac_f32_e32 v17, v77, v29
	v_fmac_f32_e32 v17, v78, v30
	v_fmac_f32_e32 v17, v79, v31
	v_fmac_f32_e32 v17, v80, v32
	v_fmac_f32_e32 v17, v81, v33
	v_fmac_f32_e32 v17, v82, v34
	v_fmac_f32_e32 v17, v83, v35
	v_fmac_f32_e32 v17, v84, v36
	v_fmac_f32_e32 v17, v85, v37
	v_fmac_f32_e32 v17, v86, v38
	v_fmac_f32_e32 v17, v87, v39
	v_fmac_f32_e32 v17, v88, v40
	v_fmac_f32_e32 v17, v89, v41
	ds_read_b128 v[74:77], v20 offset:28672
	ds_read_b128 v[78:81], v20 offset:28688
	ds_read_b128 v[82:85], v20 offset:28704
	ds_read_b128 v[86:89], v20 offset:28720
	s_waitcnt lgkmcnt(4)
	v_fmac_f32_e32 v10, v58, v26
	v_fmac_f32_e32 v10, v59, v27
	v_fmac_f32_e32 v10, v60, v28
	v_fmac_f32_e32 v10, v61, v29
	v_fmac_f32_e32 v10, v62, v30
	v_fmac_f32_e32 v10, v63, v31
	v_fmac_f32_e32 v10, v64, v32
	v_fmac_f32_e32 v10, v65, v33
	v_fmac_f32_e32 v10, v66, v34
	v_fmac_f32_e32 v10, v67, v35
	v_fmac_f32_e32 v10, v68, v36
	v_fmac_f32_e32 v10, v69, v37
	v_fmac_f32_e32 v10, v70, v38
	v_fmac_f32_e32 v10, v71, v39
	v_fmac_f32_e32 v10, v72, v40
	v_fmac_f32_e32 v10, v73, v41
	s_waitcnt lgkmcnt(0)
	v_fmac_f32_e32 v11, v74, v26
	v_fmac_f32_e32 v11, v75, v27
	v_fmac_f32_e32 v11, v76, v28
	v_fmac_f32_e32 v11, v77, v29
	v_fmac_f32_e32 v11, v78, v30
	v_fmac_f32_e32 v11, v79, v31
	v_fmac_f32_e32 v11, v80, v32
	v_fmac_f32_e32 v11, v81, v33
	v_fmac_f32_e32 v11, v82, v34
	v_fmac_f32_e32 v11, v83, v35
	v_fmac_f32_e32 v11, v84, v36
	v_fmac_f32_e32 v11, v85, v37
	v_fmac_f32_e32 v11, v86, v38
	v_fmac_f32_e32 v11, v87, v39
	v_fmac_f32_e32 v11, v88, v40
	v_fmac_f32_e32 v11, v89, v41
	v_mov_b32_e32 v20, s33
	s_add_i32 s33, s33, 64
	ds_read_b128 v[58:61], v20 offset:0
	ds_read_b128 v[62:65], v20 offset:16
	ds_read_b128 v[66:69], v20 offset:32
	ds_read_b128 v[70:73], v20 offset:48
	s_waitcnt vmcnt(0)
	ds_read_b128 v[74:77], v20 offset:4096
	ds_read_b128 v[78:81], v20 offset:4112
	ds_read_b128 v[82:85], v20 offset:4128
	ds_read_b128 v[86:89], v20 offset:4144
	s_waitcnt lgkmcnt(4)
	v_fmac_f32_e32 v12, v58, v42
	v_fmac_f32_e32 v12, v59, v43
	v_fmac_f32_e32 v12, v60, v44
	v_fmac_f32_e32 v12, v61, v45
	v_fmac_f32_e32 v12, v62, v46
	v_fmac_f32_e32 v12, v63, v47
	v_fmac_f32_e32 v12, v64, v48
	v_fmac_f32_e32 v12, v65, v49
	v_fmac_f32_e32 v12, v66, v50
	v_fmac_f32_e32 v12, v67, v51
	v_fmac_f32_e32 v12, v68, v52
	v_fmac_f32_e32 v12, v69, v53
	v_fmac_f32_e32 v12, v70, v54
	v_fmac_f32_e32 v12, v71, v55
	v_fmac_f32_e32 v12, v72, v56
	v_fmac_f32_e32 v12, v73, v57
	ds_read_b128 v[58:61], v20 offset:8192
	ds_read_b128 v[62:65], v20 offset:8208
	ds_read_b128 v[66:69], v20 offset:8224
	ds_read_b128 v[70:73], v20 offset:8240
	s_waitcnt lgkmcnt(4)
	v_fmac_f32_e32 v13, v74, v42
	v_fmac_f32_e32 v13, v75, v43
	v_fmac_f32_e32 v13, v76, v44
	v_fmac_f32_e32 v13, v77, v45
	v_fmac_f32_e32 v13, v78, v46
	v_fmac_f32_e32 v13, v79, v47
	v_fmac_f32_e32 v13, v80, v48
	v_fmac_f32_e32 v13, v81, v49
	v_fmac_f32_e32 v13, v82, v50
	v_fmac_f32_e32 v13, v83, v51
	v_fmac_f32_e32 v13, v84, v52
	v_fmac_f32_e32 v13, v85, v53
	v_fmac_f32_e32 v13, v86, v54
	v_fmac_f32_e32 v13, v87, v55
	v_fmac_f32_e32 v13, v88, v56
	v_fmac_f32_e32 v13, v89, v57
	ds_read_b128 v[74:77], v20 offset:12288
	ds_read_b128 v[78:81], v20 offset:12304
	ds_read_b128 v[82:85], v20 offset:12320
	ds_read_b128 v[86:89], v20 offset:12336
	s_waitcnt lgkmcnt(4)
	v_fmac_f32_e32 v14, v58, v42
	v_fmac_f32_e32 v14, v59, v43
	v_fmac_f32_e32 v14, v60, v44
	v_fmac_f32_e32 v14, v61, v45
	v_fmac_f32_e32 v14, v62, v46
	v_fmac_f32_e32 v14, v63, v47
	v_fmac_f32_e32 v14, v64, v48
	v_fmac_f32_e32 v14, v65, v49
	v_fmac_f32_e32 v14, v66, v50
	v_fmac_f32_e32 v14, v67, v51
	v_fmac_f32_e32 v14, v68, v52
	v_fmac_f32_e32 v14, v69, v53
	v_fmac_f32_e32 v14, v70, v54
	v_fmac_f32_e32 v14, v71, v55
	v_fmac_f32_e32 v14, v72, v56
	v_fmac_f32_e32 v14, v73, v57
	ds_read_b128 v[58:61], v20 offset:16384
	ds_read_b128 v[62:65], v20 offset:16400
	ds_read_b128 v[66:69], v20 offset:16416
	ds_read_b128 v[70:73], v20 offset:16432
	s_waitcnt lgkmcnt(4)
	v_fmac_f32_e32 v15, v74, v42
	v_fmac_f32_e32 v15, v75, v43
	v_fmac_f32_e32 v15, v76, v44
	v_fmac_f32_e32 v15, v77, v45
	v_fmac_f32_e32 v15, v78, v46
	v_fmac_f32_e32 v15, v79, v47
	v_fmac_f32_e32 v15, v80, v48
	v_fmac_f32_e32 v15, v81, v49
	v_fmac_f32_e32 v15, v82, v50
	v_fmac_f32_e32 v15, v83, v51
	v_fmac_f32_e32 v15, v84, v52
	v_fmac_f32_e32 v15, v85, v53
	v_fmac_f32_e32 v15, v86, v54
	v_fmac_f32_e32 v15, v87, v55
	v_fmac_f32_e32 v15, v88, v56
	v_fmac_f32_e32 v15, v89, v57
	ds_read_b128 v[74:77], v20 offset:20480
	ds_read_b128 v[78:81], v20 offset:20496
	ds_read_b128 v[82:85], v20 offset:20512
	ds_read_b128 v[86:89], v20 offset:20528
	s_waitcnt lgkmcnt(4)
	v_fmac_f32_e32 v16, v58, v42
	v_fmac_f32_e32 v16, v59, v43
	v_fmac_f32_e32 v16, v60, v44
	v_fmac_f32_e32 v16, v61, v45
	v_fmac_f32_e32 v16, v62, v46
	v_fmac_f32_e32 v16, v63, v47
	v_fmac_f32_e32 v16, v64, v48
	v_fmac_f32_e32 v16, v65, v49
	v_fmac_f32_e32 v16, v66, v50
	v_fmac_f32_e32 v16, v67, v51
	v_fmac_f32_e32 v16, v68, v52
	v_fmac_f32_e32 v16, v69, v53
	v_fmac_f32_e32 v16, v70, v54
	v_fmac_f32_e32 v16, v71, v55
	v_fmac_f32_e32 v16, v72, v56
	v_fmac_f32_e32 v16, v73, v57
	ds_read_b128 v[58:61], v20 offset:24576
	ds_read_b128 v[62:65], v20 offset:24592
	ds_read_b128 v[66:69], v20 offset:24608
	ds_read_b128 v[70:73], v20 offset:24624
	s_waitcnt lgkmcnt(4)
	v_fmac_f32_e32 v17, v74, v42
	v_fmac_f32_e32 v17, v75, v43
	v_fmac_f32_e32 v17, v76, v44
	v_fmac_f32_e32 v17, v77, v45
	v_fmac_f32_e32 v17, v78, v46
	v_fmac_f32_e32 v17, v79, v47
	v_fmac_f32_e32 v17, v80, v48
	v_fmac_f32_e32 v17, v81, v49
	v_fmac_f32_e32 v17, v82, v50
	v_fmac_f32_e32 v17, v83, v51
	v_fmac_f32_e32 v17, v84, v52
	v_fmac_f32_e32 v17, v85, v53
	v_fmac_f32_e32 v17, v86, v54
	v_fmac_f32_e32 v17, v87, v55
	v_fmac_f32_e32 v17, v88, v56
	v_fmac_f32_e32 v17, v89, v57
	ds_read_b128 v[74:77], v20 offset:28672
	ds_read_b128 v[78:81], v20 offset:28688
	ds_read_b128 v[82:85], v20 offset:28704
	ds_read_b128 v[86:89], v20 offset:28720
	s_waitcnt lgkmcnt(4)
	v_fmac_f32_e32 v10, v58, v42
	v_fmac_f32_e32 v10, v59, v43
	v_fmac_f32_e32 v10, v60, v44
	v_fmac_f32_e32 v10, v61, v45
	v_fmac_f32_e32 v10, v62, v46
	v_fmac_f32_e32 v10, v63, v47
	v_fmac_f32_e32 v10, v64, v48
	v_fmac_f32_e32 v10, v65, v49
	v_fmac_f32_e32 v10, v66, v50
	v_fmac_f32_e32 v10, v67, v51
	v_fmac_f32_e32 v10, v68, v52
	v_fmac_f32_e32 v10, v69, v53
	v_fmac_f32_e32 v10, v70, v54
	v_fmac_f32_e32 v10, v71, v55
	v_fmac_f32_e32 v10, v72, v56
	v_fmac_f32_e32 v10, v73, v57
	s_waitcnt lgkmcnt(0)
	v_fmac_f32_e32 v11, v74, v42
	v_fmac_f32_e32 v11, v75, v43
	v_fmac_f32_e32 v11, v76, v44
	v_fmac_f32_e32 v11, v77, v45
	v_fmac_f32_e32 v11, v78, v46
	v_fmac_f32_e32 v11, v79, v47
	v_fmac_f32_e32 v11, v80, v48
	v_fmac_f32_e32 v11, v81, v49
	v_fmac_f32_e32 v11, v82, v50
	v_fmac_f32_e32 v11, v83, v51
	v_fmac_f32_e32 v11, v84, v52
	v_fmac_f32_e32 v11, v85, v53
	v_fmac_f32_e32 v11, v86, v54
	v_fmac_f32_e32 v11, v87, v55
	v_fmac_f32_e32 v11, v88, v56
	v_fmac_f32_e32 v11, v89, v57
	s_load_dwordx16 s[36:51], s[0:1], 0x40
	v_or_b32_e32 v8, s10, v0
	v_ashrrev_i32_e32 v9, 31, v8
	v_add_u32_e32 v2, s14, v1
	ds_write2st64_b32 v2, v12, v13 offset0:128 offset1:129
	ds_write2st64_b32 v2, v14, v15 offset0:130 offset1:131
	ds_write2st64_b32 v2, v16, v17 offset0:132 offset1:133
	ds_write2st64_b32 v2, v10, v11 offset0:134 offset1:135
	s_waitcnt lgkmcnt(0)
	v_lshl_add_u64 v[8:9], v[8:9], 2, s[40:41]
	s_barrier
	global_load_dword v2, v[8:9], off
	ds_read2st64_b32 v[10:11], v24 offset0:128 offset1:136
	ds_read2st64_b32 v[12:13], v24 offset0:144 offset1:152
	ds_read2st64_b32 v[14:15], v24 offset0:160 offset1:168
	ds_read2st64_b32 v[16:17], v24 offset0:176 offset1:184
	v_lshl_add_u32 v18, s31, 3, v23
	v_mov_b64_e32 v[8:9], s[52:53]
	v_mad_i64_i32 v[8:9], s[6:7], v18, s2, v[8:9]
	v_mov_b32_e32 v7, v3
	s_add_i32 s30, s30, s15
	v_lshl_add_u64 v[8:9], s[10:11], 2, v[8:9]
	s_cmpk_gt_i32 s30, 0x11f
	v_lshl_add_u64 v[8:9], v[8:9], 0, v[6:7]
	s_waitcnt vmcnt(0) lgkmcnt(3)
	v_add_f32_e32 v2, v2, v10
	v_add_f32_e32 v2, v2, v11
	s_waitcnt lgkmcnt(2)
	v_add_f32_e32 v2, v2, v12
	v_add_f32_e32 v2, v2, v13
	s_waitcnt lgkmcnt(1)
	v_add_f32_e32 v2, v2, v14
	v_add_f32_e32 v2, v2, v15
	s_waitcnt lgkmcnt(0)
	v_add_f32_e32 v2, v2, v16
	v_add_f32_e32 v2, v2, v17
	global_store_dword v[8:9], v2, off
	s_barrier
	s_cbranch_scc0 .LBB0_18
	s_load_dword s3, s[84:85], 0x0
	s_waitcnt lgkmcnt(0)
	s_cmp_gt_u32 s3, 32
	s_cselect_b32 s4, 32, 0
	s_cmp_lt_u32 s93, s4
	s_cbranch_scc1 .Ltr_skip
	s_sub_i32 s2, s93, s4
	s_lshl_b32 s2, s2, 3
	s_lshr_b32 s5, s86, 6
	s_add_i32 s2, s2, s5
	s_sub_i32 s3, s3, s4
	s_lshl_b32 s3, s3, 3
	s_cmpk_gt_i32 s2, 0xcff
	s_cbranch_scc1 .Ltr_skip
	s_waitcnt vmcnt(0)
	s_sub_u32 s12, s84, 0xf0
	s_subb_u32 s13, s85, 0
	s_load_dwordx2 s[14:15], s[12:13], 0x58
	s_load_dwordx4 s[20:23], s[12:13], 0xc0
	s_load_dwordx2 s[26:27], s[12:13], 0xe0
	v_mbcnt_hi_u32_b32 v0, -1, v194
	v_and_b32_e32 v13, 31, v0
	v_lshrrev_b32_e32 v14, 5, v0
	s_lshr_b32 s28, s86, 6
	s_mul_i32 s28, s28, 0x2100
	v_mul_u32_u24_e32 v3, 33, v14
	v_add_u32_e32 v3, v3, v13
	v_lshl_add_u32 v3, v3, 2, s28
	v_and_b32_e32 v5, 7, v0
	v_lshrrev_b32_e32 v6, 3, v0
	v_mul_u32_u24_e32 v4, 0x108, v5
	v_add_u32_e32 v4, v4, v6
	v_lshl_add_u32 v4, v4, 2, s28
	v_lshlrev_b32_e32 v8, 2, v13
	v_lshlrev_b32_e32 v9, 5, v5
	v_lshlrev_b32_e32 v10, 4, v5
	s_waitcnt lgkmcnt(0)

.Ltr_wout:
	s_add_i32 s30, s2, 0xfffff700
	s_lshr_b32 s29, s30, 5
	s_and_b32 s30, s30, 31
	s_lshl_b32 s31, s29, 18
	s_lshl_b32 s36, s30, 7
	s_add_u32 s31, s31, s36
	s_add_u32 s34, s22, s31
	s_addc_u32 s35, s23, 0
	s_movk_i32 s36, 0x1000
	s_lshl_b32 s37, s30, 17
	s_lshl_b32 s38, s29, 7
	s_add_u32 s37, s37, s38
	s_add_u32 s37, s37, 0x8b80000
	s_add_u32 s38, s26, s37
	s_addc_u32 s39, s27, 0
	s_movk_i32 s42, 0x1000
	s_cmp_gt_u32 s29, 15
	s_cselect_b32 s43, 1, 0
	s_lshl_b32 s46, s29, 8
	s_add_i32 s46, s46, 0xfffff000
	s_ashr_i32 s47, s46, 31
	s_add_u32 s46, s20, s46
	s_addc_u32 s47, s21, s47
.Ltr_item:
	v_mad_u32_u24 v7, v14, s36, v8
	s_lshl_b32 s36, s36, 1
	v_mad_u32_u24 v12, v6, s42, v10
	s_cmp_eq_u32 s43, 0
	s_cbranch_scc1 .Ltr_nosc
	global_load_dwordx4 v[64:67], v9, s[46:47]
	global_load_dwordx4 v[68:71], v9, s[46:47] offset:16
.Ltr_nosc:
	global_load_dword v16, v7, s[34:35]
	s_add_u32 s34, s34, s36
	s_addc_u32 s35, s35, 0
	global_load_dword v17, v7, s[34:35]
	s_add_u32 s34, s34, s36
	s_addc_u32 s35, s35, 0
	global_load_dword v18, v7, s[34:35]
	s_add_u32 s34, s34, s36
	s_addc_u32 s35, s35, 0
	global_load_dword v19, v7, s[34:35]
	s_add_u32 s34, s34, s36
	s_addc_u32 s35, s35, 0
	global_load_dword v20, v7, s[34:35]
	s_add_u32 s34, s34, s36
	s_addc_u32 s35, s35, 0
	global_load_dword v21, v7, s[34:35]
	s_add_u32 s34, s34, s36
	s_addc_u32 s35, s35, 0
	global_load_dword v22, v7, s[34:35]
	s_add_u32 s34, s34, s36
	s_addc_u32 s35, s35, 0
	global_load_dword v23, v7, s[34:35]
	s_add_u32 s34, s34, s36
	s_addc_u32 s35, s35, 0
	global_load_dword v24, v7, s[34:35]
	s_add_u32 s34, s34, s36
	s_addc_u32 s35, s35, 0
	global_load_dword v25, v7, s[34:35]
	s_add_u32 s34, s34, s36
	s_addc_u32 s35, s35, 0
	global_load_dword v26, v7, s[34:35]
	s_add_u32 s34, s34, s36
	s_addc_u32 s35, s35, 0
	global_load_dword v27, v7, s[34:35]
	s_add_u32 s34, s34, s36
	s_addc_u32 s35, s35, 0
	global_load_dword v28, v7, s[34:35]
	s_add_u32 s34, s34, s36
	s_addc_u32 s35, s35, 0
	global_load_dword v29, v7, s[34:35]
	s_add_u32 s34, s34, s36
	s_addc_u32 s35, s35, 0
	global_load_dword v30, v7, s[34:35]
	s_add_u32 s34, s34, s36
	s_addc_u32 s35, s35, 0
	global_load_dword v31, v7, s[34:35]
	s_add_u32 s34, s34, s36
	s_addc_u32 s35, s35, 0
	global_load_dword v32, v7, s[34:35]
	s_add_u32 s34, s34, s36
	s_addc_u32 s35, s35, 0
	global_load_dword v33, v7, s[34:35]
	s_add_u32 s34, s34, s36
	s_addc_u32 s35, s35, 0
	global_load_dword v34, v7, s[34:35]
	s_add_u32 s34, s34, s36
	s_addc_u32 s35, s35, 0
	global_load_dword v35, v7, s[34:35]
	s_add_u32 s34, s34, s36
	s_addc_u32 s35, s35, 0
	global_load_dword v36, v7, s[34:35]
	s_add_u32 s34, s34, s36
	s_addc_u32 s35, s35, 0
	global_load_dword v37, v7, s[34:35]
	s_add_u32 s34, s34, s36
	s_addc_u32 s35, s35, 0
	global_load_dword v38, v7, s[34:35]
	s_add_u32 s34, s34, s36
	s_addc_u32 s35, s35, 0
	global_load_dword v39, v7, s[34:35]
	s_add_u32 s34, s34, s36
	s_addc_u32 s35, s35, 0
	global_load_dword v40, v7, s[34:35]
	s_add_u32 s34, s34, s36
	s_addc_u32 s35, s35, 0
	global_load_dword v41, v7, s[34:35]
	s_add_u32 s34, s34, s36
	s_addc_u32 s35, s35, 0
	global_load_dword v42, v7, s[34:35]
	s_add_u32 s34, s34, s36
	s_addc_u32 s35, s35, 0
	global_load_dword v43, v7, s[34:35]
	s_add_u32 s34, s34, s36
	s_addc_u32 s35, s35, 0
	global_load_dword v44, v7, s[34:35]
	s_add_u32 s34, s34, s36
	s_addc_u32 s35, s35, 0
	global_load_dword v45, v7, s[34:35]
	s_add_u32 s34, s34, s36
	s_addc_u32 s35, s35, 0
	global_load_dword v46, v7, s[34:35]
	s_add_u32 s34, s34, s36
	s_addc_u32 s35, s35, 0
	global_load_dword v47, v7, s[34:35]
	s_add_u32 s34, s34, s36
	s_addc_u32 s35, s35, 0
	s_waitcnt vmcnt(0)
	ds_write_b32 v3, v16
	ds_write_b32 v3, v17 offset:264
	ds_write_b32 v3, v18 offset:528
	ds_write_b32 v3, v19 offset:792
	ds_write_b32 v3, v20 offset:1056
	ds_write_b32 v3, v21 offset:1320
	ds_write_b32 v3, v22 offset:1584
	ds_write_b32 v3, v23 offset:1848
	ds_write_b32 v3, v24 offset:2112
	ds_write_b32 v3, v25 offset:2376
	ds_write_b32 v3, v26 offset:2640
	ds_write_b32 v3, v27 offset:2904
	ds_write_b32 v3, v28 offset:3168
	ds_write_b32 v3, v29 offset:3432
	ds_write_b32 v3, v30 offset:3696
	ds_write_b32 v3, v31 offset:3960
	ds_write_b32 v3, v32 offset:4224
	ds_write_b32 v3, v33 offset:4488
	ds_write_b32 v3, v34 offset:4752
	ds_write_b32 v3, v35 offset:5016
	ds_write_b32 v3, v36 offset:5280
	ds_write_b32 v3, v37 offset:5544
	ds_write_b32 v3, v38 offset:5808
	ds_write_b32 v3, v39 offset:6072
	ds_write_b32 v3, v40 offset:6336
	ds_write_b32 v3, v41 offset:6600
	ds_write_b32 v3, v42 offset:6864
	ds_write_b32 v3, v43 offset:7128
	ds_write_b32 v3, v44 offset:7392
	ds_write_b32 v3, v45 offset:7656
	ds_write_b32 v3, v46 offset:7920
	ds_write_b32 v3, v47 offset:8184
	s_waitcnt lgkmcnt(0)
	s_lshl_b32 s42, s42, 3
	ds_read2_b32 v[72:73], v4 offset0:0 offset1:33
	ds_read2_b32 v[74:75], v4 offset0:66 offset1:99
	ds_read2_b32 v[76:77], v4 offset0:132 offset1:165
	ds_read2_b32 v[78:79], v4 offset0:198 offset1:231
	s_waitcnt lgkmcnt(0)
	s_cmp_eq_u32 s43, 0
	s_cbranch_scc1 .Ltr_ns0
	v_mul_f32_e32 v72, v72, v64
	v_mul_f32_e32 v73, v73, v65
	v_mul_f32_e32 v74, v74, v66
	v_mul_f32_e32 v75, v75, v67
	v_mul_f32_e32 v76, v76, v68
	v_mul_f32_e32 v77, v77, v69
	v_mul_f32_e32 v78, v78, v70
	v_mul_f32_e32 v79, v79, v71
.Ltr_ns0:
	v_cvt_pk_bf16_f32 v44, v72, v73
	v_cvt_pk_bf16_f32 v45, v74, v75
	v_cvt_pk_bf16_f32 v46, v76, v77
	v_cvt_pk_bf16_f32 v47, v78, v79
	global_store_dwordx4 v12, v[44:47], s[38:39]
	s_add_u32 s38, s38, s42
	s_addc_u32 s39, s39, 0
	ds_read2_b32 v[72:73], v4 offset0:8 offset1:41
	ds_read2_b32 v[74:75], v4 offset0:74 offset1:107
	ds_read2_b32 v[76:77], v4 offset0:140 offset1:173
	ds_read2_b32 v[78:79], v4 offset0:206 offset1:239
	s_waitcnt lgkmcnt(0)
	s_cmp_eq_u32 s43, 0
	s_cbranch_scc1 .Ltr_ns1
	v_mul_f32_e32 v72, v72, v64
	v_mul_f32_e32 v73, v73, v65
	v_mul_f32_e32 v74, v74, v66
	v_mul_f32_e32 v75, v75, v67
	v_mul_f32_e32 v76, v76, v68
	v_mul_f32_e32 v77, v77, v69
	v_mul_f32_e32 v78, v78, v70
	v_mul_f32_e32 v79, v79, v71
.Ltr_ns1:
	v_cvt_pk_bf16_f32 v44, v72, v73
	v_cvt_pk_bf16_f32 v45, v74, v75
	v_cvt_pk_bf16_f32 v46, v76, v77
	v_cvt_pk_bf16_f32 v47, v78, v79
	global_store_dwordx4 v12, v[44:47], s[38:39]
	s_add_u32 s38, s38, s42
	s_addc_u32 s39, s39, 0
	ds_read2_b32 v[72:73], v4 offset0:16 offset1:49
	ds_read2_b32 v[74:75], v4 offset0:82 offset1:115
	ds_read2_b32 v[76:77], v4 offset0:148 offset1:181
	ds_read2_b32 v[78:79], v4 offset0:214 offset1:247
	s_waitcnt lgkmcnt(0)
	s_cmp_eq_u32 s43, 0
	s_cbranch_scc1 .Ltr_ns2
	v_mul_f32_e32 v72, v72, v64
	v_mul_f32_e32 v73, v73, v65
	v_mul_f32_e32 v74, v74, v66
	v_mul_f32_e32 v75, v75, v67
	v_mul_f32_e32 v76, v76, v68
	v_mul_f32_e32 v77, v77, v69
	v_mul_f32_e32 v78, v78, v70
	v_mul_f32_e32 v79, v79, v71
.Ltr_ns2:
	v_cvt_pk_bf16_f32 v44, v72, v73
	v_cvt_pk_bf16_f32 v45, v74, v75
	v_cvt_pk_bf16_f32 v46, v76, v77
	v_cvt_pk_bf16_f32 v47, v78, v79
	global_store_dwordx4 v12, v[44:47], s[38:39]
	s_add_u32 s38, s38, s42
	s_addc_u32 s39, s39, 0
	ds_read2_b32 v[72:73], v4 offset0:24 offset1:57
	ds_read2_b32 v[74:75], v4 offset0:90 offset1:123
	ds_read2_b32 v[76:77], v4 offset0:156 offset1:189
	ds_read2_b32 v[78:79], v4 offset0:222 offset1:255
	s_waitcnt lgkmcnt(0)
	s_cmp_eq_u32 s43, 0
	s_cbranch_scc1 .Ltr_ns3
	v_mul_f32_e32 v72, v72, v64
	v_mul_f32_e32 v73, v73, v65
	v_mul_f32_e32 v74, v74, v66
	v_mul_f32_e32 v75, v75, v67
	v_mul_f32_e32 v76, v76, v68
	v_mul_f32_e32 v77, v77, v69
	v_mul_f32_e32 v78, v78, v70
	v_mul_f32_e32 v79, v79, v71
.Ltr_ns3:
	v_cvt_pk_bf16_f32 v44, v72, v73
	v_cvt_pk_bf16_f32 v45, v74, v75
	v_cvt_pk_bf16_f32 v46, v76, v77
	v_cvt_pk_bf16_f32 v47, v78, v79
	global_store_dwordx4 v12, v[44:47], s[38:39]
	s_add_u32 s38, s38, s42
	s_addc_u32 s39, s39, 0
	s_add_i32 s2, s2, s3
	s_cmpk_lt_i32 s2, 0xd00
	s_cbranch_scc1 .Ltr_loop
.Ltr_skip:
.LBB0_28:
	s_add_u32 s2, s52, 0x3c5e0000
	s_addc_u32 s3, s53, 0
	s_cmp_gt_i32 s55, 1
	v_writelane_b32 v254, s2, 32
	s_cselect_b64 s[4:5], -1, 0
	s_nop 0
	v_writelane_b32 v254, s3, 33
	s_and_b64 s[2:3], s[8:9], s[4:5]
	s_andn2_b64 vcc, exec, s[2:3]
	s_cbranch_vccnz .LBB0_40
	s_waitcnt vmcnt(0) lgkmcnt(0)
	v_mbcnt_hi_u32_b32 v0, -1, v194
	v_or_b32_e32 v0, s86, v0
	v_cmp_eq_u32_e32 vcc, 0, v0
	s_barrier
	s_and_saveexec_b64 s[6:7], vcc
	s_cbranch_execz .LBB0_39
	s_load_dword s12, s[84:85], 0x0
	s_mov_b64 s[8:9], exec
	buffer_wbl2 sc1
	s_waitcnt vmcnt(0) lgkmcnt(0)
	s_waitcnt vmcnt(0)
	v_mbcnt_lo_u32_b32 v0, s8, 0
	v_mbcnt_hi_u32_b32 v0, s9, v0
	s_and_b32 s3, s93, 31
	v_cmp_eq_u32_e32 vcc, 0, v0
	s_and_saveexec_b64 s[10:11], vcc
	s_cbranch_execz .LBB0_32
	s_bcnt1_i32_b64 s8, s[8:9]
	s_lshl_b32 s2, s3, 7
	v_mov_b32_e32 v2, s8
	v_readlane_b32 s8, v254, 32
	v_mov_b32_e32 v1, s2
	v_readlane_b32 s9, v254, 33
	s_nop 4
	global_atomic_add v1, v1, v2, s[8:9] sc0

.LBB0_61:
	s_cmpk_gt_i32 s2, 0xcff
	s_barrier
	s_cbranch_scc1 .LBB0_104
.LBB0_104:
	v_readlane_b32 s0, v254, 50
	v_readlane_b32 s3, v254, 53
	v_readlane_b32 s1, v254, 51
	s_cmp_gt_i32 s3, 2
	v_readlane_b32 s2, v254, 52
	s_cselect_b64 s[0:1], -1, 0
	s_and_b64 s[2:3], s[10:11], s[0:1]
	s_andn2_b64 vcc, exec, s[2:3]
	s_cbranch_vccnz .LBB0_116
	s_waitcnt vmcnt(0) lgkmcnt(0)
	s_waitcnt vmcnt(3)
	v_mbcnt_hi_u32_b32 v0, -1, v194
	v_or_b32_e32 v0, s86, v0
	s_add_i32 s94, s94, 1
	v_cmp_eq_u32_e32 vcc, 0, v0
	s_barrier
	s_and_saveexec_b64 s[4:5], vcc
	s_cbranch_execz .LBB0_115
	s_load_dword s14, s[84:85], 0x0
	s_mov_b64 s[10:11], exec
	buffer_wbl2 sc1
	s_waitcnt vmcnt(0) lgkmcnt(0)
	s_waitcnt vmcnt(0)
	v_mbcnt_lo_u32_b32 v0, s10, 0
	v_mbcnt_hi_u32_b32 v0, s11, v0
	s_and_b32 s3, s93, 31
	v_cmp_eq_u32_e32 vcc, 0, v0
	s_and_saveexec_b64 s[12:13], vcc
	s_cbranch_execz .LBB0_108
	s_bcnt1_i32_b64 s10, s[10:11]
	s_lshl_b32 s2, s3, 7
	v_mov_b32_e32 v2, s10
	v_readlane_b32 s10, v254, 32
	v_mov_b32_e32 v1, s2
	v_readlane_b32 s11, v254, 33
	s_nop 4
	global_atomic_add v1, v1, v2, s[10:11] sc0
